# attention LDS prefetch depth + GQA head map + GEMM K-loops: saddr LDS-DMA and 3 of 6 SP2 pieces issued inside MFMA block (all 8 loops)
# baseline (speedup 1.0000x reference)
.LBB0_168:
	s_add_u32 s46, s66, 0xfff80080
	s_addc_u32 s47, s67, -1
	s_add_i32 s62, 0, 0x10000
	s_cmp_eq_u32 s82, 28
	s_cselect_b32 s69, s17, s47
	s_cselect_b32 s68, s65, s46
	v_add_u32_e32 v143, s62, v140
	s_cselect_b32 s61, s13, s81
	s_cselect_b32 s60, s79, s80
	s_add_i32 s63, 0, 0x14000
	ds_read_b128 v[144:147], v143
	ds_read_b128 v[148:151], v143 offset:1024
	ds_read_b128 v[152:155], v143 offset:2048
	ds_read_b128 v[156:159], v143 offset:3072
	v_add_u32_e32 v143, s63, v140
	ds_read_b128 v[160:163], v143
	ds_read_b128 v[178:181], v143 offset:1024
	ds_read_b128 v[182:185], v143 offset:2048
	ds_read_b128 v[186:189], v143 offset:3072
	s_add_i32 m0, s19, 0xc000
	ds_read_b128 v[206:209], v142
	ds_read_b128 v[210:213], v142 offset:1024
	ds_read_b128 v[214:217], v142 offset:2048
	ds_read_b128 v[218:221], v142 offset:3072
	ds_read_b128 v[222:225], v142 offset:4096
	ds_read_b128 v[226:229], v142 offset:5120
	ds_read_b128 v[230:233], v142 offset:6144
	ds_read_b128 v[234:237], v142 offset:7168
	global_load_lds_dwordx4 v136, s[66:67]
	s_add_i32 m0, s19, 0xe000
	s_nop 0
	global_load_lds_dwordx4 v138, s[66:67]
	s_waitcnt vmcnt(8)
	s_waitcnt lgkmcnt(0)
	s_barrier
	s_setprio 1
	s_waitcnt lgkmcnt(0)
	v_mfma_f32_16x16x32_bf16 v[126:129], v[144:147], v[206:209], v[126:129]
	v_mfma_f32_16x16x32_bf16 v[122:125], v[152:155], v[206:209], v[122:125]
	v_mfma_f32_16x16x32_bf16 v[118:121], v[144:147], v[214:217], v[118:121]
	v_mfma_f32_16x16x32_bf16 v[114:117], v[152:155], v[214:217], v[114:117]
	v_mfma_f32_16x16x32_bf16 v[102:105], v[144:147], v[222:225], v[102:105]
	v_mfma_f32_16x16x32_bf16 v[98:101], v[152:155], v[222:225], v[98:101]
	v_mfma_f32_16x16x32_bf16 v[86:89], v[144:147], v[230:233], v[86:89]
	v_mfma_f32_16x16x32_bf16 v[82:85], v[152:155], v[230:233], v[82:85]
	v_mfma_f32_16x16x32_bf16 v[126:129], v[148:151], v[210:213], v[126:129]
	v_mfma_f32_16x16x32_bf16 v[122:125], v[156:159], v[210:213], v[122:125]
	v_mfma_f32_16x16x32_bf16 v[118:121], v[148:151], v[218:221], v[118:121]
	v_mfma_f32_16x16x32_bf16 v[114:117], v[156:159], v[218:221], v[114:117]
	v_mfma_f32_16x16x32_bf16 v[102:105], v[148:151], v[226:229], v[102:105]
	v_mfma_f32_16x16x32_bf16 v[98:101], v[156:159], v[226:229], v[98:101]
	v_mfma_f32_16x16x32_bf16 v[86:89], v[148:151], v[234:237], v[86:89]
	v_mfma_f32_16x16x32_bf16 v[82:85], v[156:159], v[234:237], v[82:85]
	s_setprio 0
	s_setprio 1
	v_mfma_f32_16x16x32_bf16 v[110:113], v[160:163], v[206:209], v[110:113]
	v_mfma_f32_16x16x32_bf16 v[106:109], v[182:185], v[206:209], v[106:109]
	v_mfma_f32_16x16x32_bf16 v[94:97], v[160:163], v[214:217], v[94:97]
	v_mfma_f32_16x16x32_bf16 v[90:93], v[182:185], v[214:217], v[90:93]
	v_mfma_f32_16x16x32_bf16 v[78:81], v[160:163], v[222:225], v[78:81]
	v_mfma_f32_16x16x32_bf16 v[74:77], v[182:185], v[222:225], v[74:77]
	v_mfma_f32_16x16x32_bf16 v[70:73], v[160:163], v[230:233], v[70:73]
	v_mfma_f32_16x16x32_bf16 v[66:69], v[182:185], v[230:233], v[66:69]
	v_mfma_f32_16x16x32_bf16 v[110:113], v[178:181], v[210:213], v[110:113]
	v_mfma_f32_16x16x32_bf16 v[106:109], v[186:189], v[210:213], v[106:109]
	v_mfma_f32_16x16x32_bf16 v[94:97], v[178:181], v[218:221], v[94:97]
	v_mfma_f32_16x16x32_bf16 v[90:93], v[186:189], v[218:221], v[90:93]
	v_mfma_f32_16x16x32_bf16 v[78:81], v[178:181], v[226:229], v[78:81]
	v_mfma_f32_16x16x32_bf16 v[74:77], v[186:189], v[226:229], v[74:77]
	v_mfma_f32_16x16x32_bf16 v[70:73], v[178:181], v[234:237], v[70:73]
	v_mfma_f32_16x16x32_bf16 v[66:69], v[186:189], v[234:237], v[66:69]
	s_setprio 0
	s_barrier
	s_add_i32 s46, s62, s71
	s_mov_b32 m0, s46
	ds_read_b128 v[206:209], v142 offset:16384
	ds_read_b128 v[210:213], v142 offset:17408
	ds_read_b128 v[214:217], v142 offset:18432
	ds_read_b128 v[218:221], v142 offset:19456
	ds_read_b128 v[222:225], v142 offset:20480
	ds_read_b128 v[226:229], v142 offset:21504
	ds_read_b128 v[230:233], v142 offset:22528
	ds_read_b128 v[234:237], v142 offset:23552
	global_load_lds_dwordx4 v166, s[60:61]
	s_add_i32 m0, s46, 0x2000
	s_add_u32 s46, s60, 0x80000
	v_lshl_add_u64 v[242:243], s[60:61], 0, v[130:131]
	s_addc_u32 s47, s61, 0
	s_add_i32 s62, s63, s71
	global_load_lds_dwordx4 v130, s[60:61]
	s_mov_b32 m0, s62
	s_nop 0
	global_load_lds_dwordx4 v166, s[46:47]
	s_waitcnt vmcnt(5)
	s_waitcnt lgkmcnt(0)
	s_barrier
	s_setprio 1
	s_waitcnt lgkmcnt(0)
	v_mfma_f32_16x16x32_bf16 v[62:65], v[144:147], v[206:209], v[62:65]
	v_mfma_f32_16x16x32_bf16 v[58:61], v[152:155], v[206:209], v[58:61]
	v_mfma_f32_16x16x32_bf16 v[54:57], v[144:147], v[214:217], v[54:57]
	v_mfma_f32_16x16x32_bf16 v[50:53], v[152:155], v[214:217], v[50:53]
	v_mfma_f32_16x16x32_bf16 v[38:41], v[144:147], v[222:225], v[38:41]
	v_mfma_f32_16x16x32_bf16 v[34:37], v[152:155], v[222:225], v[34:37]
	s_add_i32 m0, s62, 0x2000
	s_nop 0
	global_load_lds_dwordx4 v130, s[46:47]
	v_mfma_f32_16x16x32_bf16 v[22:25], v[144:147], v[230:233], v[22:25]
	v_mfma_f32_16x16x32_bf16 v[18:21], v[152:155], v[230:233], v[18:21]
	v_mfma_f32_16x16x32_bf16 v[62:65], v[148:151], v[210:213], v[62:65]
	v_mfma_f32_16x16x32_bf16 v[58:61], v[156:159], v[210:213], v[58:61]
	v_mfma_f32_16x16x32_bf16 v[54:57], v[148:151], v[218:221], v[54:57]
	v_mfma_f32_16x16x32_bf16 v[50:53], v[156:159], v[218:221], v[50:53]
	v_mfma_f32_16x16x32_bf16 v[38:41], v[148:151], v[226:229], v[38:41]
	v_mfma_f32_16x16x32_bf16 v[34:37], v[156:159], v[226:229], v[34:37]
	v_mfma_f32_16x16x32_bf16 v[22:25], v[148:151], v[234:237], v[22:25]
	v_mfma_f32_16x16x32_bf16 v[18:21], v[156:159], v[234:237], v[18:21]
	s_mov_b32 m0, s19
	s_nop 0
	global_load_lds_dwordx4 v134, s[68:69]
	s_setprio 0
	s_setprio 1
	v_mfma_f32_16x16x32_bf16 v[46:49], v[160:163], v[206:209], v[46:49]
	v_mfma_f32_16x16x32_bf16 v[42:45], v[182:185], v[206:209], v[42:45]
	v_mfma_f32_16x16x32_bf16 v[30:33], v[160:163], v[214:217], v[30:33]
	v_mfma_f32_16x16x32_bf16 v[26:29], v[182:185], v[214:217], v[26:29]
	v_mfma_f32_16x16x32_bf16 v[14:17], v[160:163], v[222:225], v[14:17]
	v_mfma_f32_16x16x32_bf16 v[10:13], v[182:185], v[222:225], v[10:13]
	v_mfma_f32_16x16x32_bf16 v[6:9], v[160:163], v[230:233], v[6:9]
	v_mfma_f32_16x16x32_bf16 v[2:5], v[182:185], v[230:233], v[2:5]
	v_mfma_f32_16x16x32_bf16 v[46:49], v[178:181], v[210:213], v[46:49]
	v_mfma_f32_16x16x32_bf16 v[42:45], v[186:189], v[210:213], v[42:45]
	s_mov_b32 m0, s73
	s_nop 0
	global_load_lds_dwordx4 v132, s[68:69]
	v_mfma_f32_16x16x32_bf16 v[30:33], v[178:181], v[218:221], v[30:33]
	v_mfma_f32_16x16x32_bf16 v[26:29], v[186:189], v[218:221], v[26:29]
	v_mfma_f32_16x16x32_bf16 v[14:17], v[178:181], v[226:229], v[14:17]
	v_mfma_f32_16x16x32_bf16 v[10:13], v[186:189], v[226:229], v[10:13]
	v_mfma_f32_16x16x32_bf16 v[6:9], v[178:181], v[234:237], v[6:9]
	v_mfma_f32_16x16x32_bf16 v[2:5], v[186:189], v[234:237], v[2:5]
	s_setprio 0
	s_barrier
	s_add_i32 s62, 0, 0x18000
	v_add_u32_e32 v143, s62, v140
	s_add_i32 s63, 0, 0x1c000
	ds_read_b128 v[144:147], v143
	ds_read_b128 v[148:151], v143 offset:1024
	ds_read_b128 v[152:155], v143 offset:2048
	ds_read_b128 v[156:159], v143 offset:3072
	v_add_u32_e32 v143, s63, v140
	ds_read_b128 v[160:163], v143
	ds_read_b128 v[178:181], v143 offset:1024
	ds_read_b128 v[182:185], v143 offset:2048
	ds_read_b128 v[186:189], v143 offset:3072
	s_add_u32 s46, s68, 0x80000
	s_addc_u32 s47, s69, 0
	s_mov_b32 m0, s74
	ds_read_b128 v[206:209], v142 offset:32768
	ds_read_b128 v[210:213], v142 offset:33792
	ds_read_b128 v[214:217], v142 offset:34816
	ds_read_b128 v[218:221], v142 offset:35840
	ds_read_b128 v[222:225], v142 offset:36864
	ds_read_b128 v[226:229], v142 offset:37888
	ds_read_b128 v[230:233], v142 offset:38912
	ds_read_b128 v[234:237], v142 offset:39936
	global_load_lds_dwordx4 v134, s[46:47]
	s_mov_b32 m0, s75
	s_nop 0
	global_load_lds_dwordx4 v132, s[46:47]
	s_waitcnt vmcnt(8)
	s_waitcnt lgkmcnt(0)
	s_barrier
	s_setprio 1
	s_waitcnt lgkmcnt(0)
	v_mfma_f32_16x16x32_bf16 v[126:129], v[144:147], v[206:209], v[126:129]
	v_mfma_f32_16x16x32_bf16 v[122:125], v[152:155], v[206:209], v[122:125]
	v_mfma_f32_16x16x32_bf16 v[118:121], v[144:147], v[214:217], v[118:121]
	v_mfma_f32_16x16x32_bf16 v[114:117], v[152:155], v[214:217], v[114:117]
	v_mfma_f32_16x16x32_bf16 v[102:105], v[144:147], v[222:225], v[102:105]
	v_mfma_f32_16x16x32_bf16 v[98:101], v[152:155], v[222:225], v[98:101]
	v_mfma_f32_16x16x32_bf16 v[86:89], v[144:147], v[230:233], v[86:89]
	v_mfma_f32_16x16x32_bf16 v[82:85], v[152:155], v[230:233], v[82:85]
	v_mfma_f32_16x16x32_bf16 v[126:129], v[148:151], v[210:213], v[126:129]
	v_mfma_f32_16x16x32_bf16 v[122:125], v[156:159], v[210:213], v[122:125]
	v_mfma_f32_16x16x32_bf16 v[118:121], v[148:151], v[218:221], v[118:121]
	v_mfma_f32_16x16x32_bf16 v[114:117], v[156:159], v[218:221], v[114:117]
	v_mfma_f32_16x16x32_bf16 v[102:105], v[148:151], v[226:229], v[102:105]
	v_mfma_f32_16x16x32_bf16 v[98:101], v[156:159], v[226:229], v[98:101]
	v_mfma_f32_16x16x32_bf16 v[86:89], v[148:151], v[234:237], v[86:89]
	v_mfma_f32_16x16x32_bf16 v[82:85], v[156:159], v[234:237], v[82:85]
	s_setprio 0
	s_setprio 1
	v_mfma_f32_16x16x32_bf16 v[110:113], v[160:163], v[206:209], v[110:113]
	v_mfma_f32_16x16x32_bf16 v[106:109], v[182:185], v[206:209], v[106:109]
	v_mfma_f32_16x16x32_bf16 v[94:97], v[160:163], v[214:217], v[94:97]
	v_mfma_f32_16x16x32_bf16 v[90:93], v[182:185], v[214:217], v[90:93]
	v_mfma_f32_16x16x32_bf16 v[78:81], v[160:163], v[222:225], v[78:81]
	v_mfma_f32_16x16x32_bf16 v[74:77], v[182:185], v[222:225], v[74:77]
	v_mfma_f32_16x16x32_bf16 v[70:73], v[160:163], v[230:233], v[70:73]
	v_mfma_f32_16x16x32_bf16 v[66:69], v[182:185], v[230:233], v[66:69]
	v_mfma_f32_16x16x32_bf16 v[110:113], v[178:181], v[210:213], v[110:113]
	v_mfma_f32_16x16x32_bf16 v[106:109], v[186:189], v[210:213], v[106:109]
	v_mfma_f32_16x16x32_bf16 v[94:97], v[178:181], v[218:221], v[94:97]
	v_mfma_f32_16x16x32_bf16 v[90:93], v[186:189], v[218:221], v[90:93]
	v_mfma_f32_16x16x32_bf16 v[78:81], v[178:181], v[226:229], v[78:81]
	v_mfma_f32_16x16x32_bf16 v[74:77], v[186:189], v[226:229], v[74:77]
	v_mfma_f32_16x16x32_bf16 v[70:73], v[178:181], v[234:237], v[70:73]
	v_mfma_f32_16x16x32_bf16 v[66:69], v[186:189], v[234:237], v[66:69]
	s_setprio 0
	s_barrier
	s_add_i32 s46, s62, s71
	s_mov_b32 m0, s46
	ds_read_b128 v[206:209], v142 offset:49152
	ds_read_b128 v[210:213], v142 offset:50176
	ds_read_b128 v[214:217], v142 offset:51200
	ds_read_b128 v[218:221], v142 offset:52224
	ds_read_b128 v[222:225], v142 offset:53248
	ds_read_b128 v[226:229], v142 offset:54272
	ds_read_b128 v[230:233], v142 offset:55296
	ds_read_b128 v[234:237], v142 offset:56320
	s_add_u32 s100, s60, 128
	s_addc_u32 s101, s61, 0
	global_load_lds_dwordx4 v166, s[100:101]
	s_add_i32 m0, s46, 0x2000
	s_add_u32 s46, s60, 0x80080
	v_lshl_add_u64 v[164:165], v[242:243], 0, s[42:43]
	s_addc_u32 s47, s61, 0
	s_add_i32 s60, s63, s71
	global_load_lds_dwordx4 v[164:165], off
	s_mov_b32 m0, s60
	s_nop 0
	global_load_lds_dwordx4 v166, s[46:47]
	s_waitcnt vmcnt(5)
	s_waitcnt lgkmcnt(0)
	s_barrier
	s_setprio 1
	s_waitcnt lgkmcnt(0)
	v_mfma_f32_16x16x32_bf16 v[62:65], v[144:147], v[206:209], v[62:65]
	v_mfma_f32_16x16x32_bf16 v[58:61], v[152:155], v[206:209], v[58:61]
	v_mfma_f32_16x16x32_bf16 v[54:57], v[144:147], v[214:217], v[54:57]
	v_mfma_f32_16x16x32_bf16 v[50:53], v[152:155], v[214:217], v[50:53]
	v_mfma_f32_16x16x32_bf16 v[38:41], v[144:147], v[222:225], v[38:41]
	v_mfma_f32_16x16x32_bf16 v[34:37], v[152:155], v[222:225], v[34:37]
	s_add_i32 m0, s60, 0x2000
	s_nop 0
	global_load_lds_dwordx4 v130, s[46:47]
	v_mfma_f32_16x16x32_bf16 v[22:25], v[144:147], v[230:233], v[22:25]
	v_mfma_f32_16x16x32_bf16 v[18:21], v[152:155], v[230:233], v[18:21]
	v_mfma_f32_16x16x32_bf16 v[62:65], v[148:151], v[210:213], v[62:65]
	v_mfma_f32_16x16x32_bf16 v[58:61], v[156:159], v[210:213], v[58:61]
	v_mfma_f32_16x16x32_bf16 v[54:57], v[148:151], v[218:221], v[54:57]
	v_mfma_f32_16x16x32_bf16 v[50:53], v[156:159], v[218:221], v[50:53]
	v_mfma_f32_16x16x32_bf16 v[38:41], v[148:151], v[226:229], v[38:41]
	v_mfma_f32_16x16x32_bf16 v[34:37], v[156:159], v[226:229], v[34:37]
	v_mfma_f32_16x16x32_bf16 v[22:25], v[148:151], v[234:237], v[22:25]
	v_mfma_f32_16x16x32_bf16 v[18:21], v[156:159], v[234:237], v[18:21]
	s_mov_b32 m0, s76
	s_nop 0
	s_add_u32 s100, s68, 128
	s_addc_u32 s101, s69, 0
	global_load_lds_dwordx4 v134, s[100:101]
	s_setprio 0
	s_setprio 1
	v_mfma_f32_16x16x32_bf16 v[46:49], v[160:163], v[206:209], v[46:49]
	v_mfma_f32_16x16x32_bf16 v[42:45], v[182:185], v[206:209], v[42:45]
	v_mfma_f32_16x16x32_bf16 v[30:33], v[160:163], v[214:217], v[30:33]
	v_mfma_f32_16x16x32_bf16 v[26:29], v[182:185], v[214:217], v[26:29]
	v_mfma_f32_16x16x32_bf16 v[14:17], v[160:163], v[222:225], v[14:17]
	v_mfma_f32_16x16x32_bf16 v[10:13], v[182:185], v[222:225], v[10:13]
	v_mfma_f32_16x16x32_bf16 v[6:9], v[160:163], v[230:233], v[6:9]
	v_mfma_f32_16x16x32_bf16 v[2:5], v[182:185], v[230:233], v[2:5]
	v_mfma_f32_16x16x32_bf16 v[46:49], v[178:181], v[210:213], v[46:49]
	v_mfma_f32_16x16x32_bf16 v[42:45], v[186:189], v[210:213], v[42:45]
	s_mov_b32 m0, s77
	s_nop 0
	s_add_u32 s100, s68, 128
	s_addc_u32 s101, s69, 0
	global_load_lds_dwordx4 v132, s[100:101]
	v_mfma_f32_16x16x32_bf16 v[30:33], v[178:181], v[218:221], v[30:33]
	v_mfma_f32_16x16x32_bf16 v[26:29], v[186:189], v[218:221], v[26:29]
	v_mfma_f32_16x16x32_bf16 v[14:17], v[178:181], v[226:229], v[14:17]
	v_mfma_f32_16x16x32_bf16 v[10:13], v[186:189], v[226:229], v[10:13]
	v_mfma_f32_16x16x32_bf16 v[6:9], v[178:181], v[234:237], v[6:9]
	v_mfma_f32_16x16x32_bf16 v[2:5], v[186:189], v[234:237], v[2:5]
	s_setprio 0
	s_barrier
	s_add_i32 s82, s82, 2
	s_add_u32 s66, s66, 0x100
	s_addc_u32 s67, s67, 0
	s_add_u32 s80, s80, 0x100
	s_addc_u32 s81, s81, 0
	s_cmp_gt_u32 s82, 29
	s_cbranch_scc0 .LBB0_168
	s_and_b64 vcc, exec, s[10:11]
	s_cbranch_vccz .LBB0_171
	s_barrier

.LBB0_426:
	s_add_u32 s46, s66, 0xfffe0080
	s_addc_u32 s47, s67, -1
	s_add_i32 s62, 0, 0x10000
	s_cmp_eq_u32 s84, 4
	s_cselect_b32 s69, s19, s47
	s_cselect_b32 s68, s80, s46
	v_add_u32_e32 v143, s62, v140
	s_cselect_b32 s61, s17, s83
	s_cselect_b32 s60, s81, s82
	s_add_i32 s63, 0, 0x14000
	ds_read_b128 v[144:147], v143
	ds_read_b128 v[148:151], v143 offset:1024
	ds_read_b128 v[152:155], v143 offset:2048
	ds_read_b128 v[156:159], v143 offset:3072
	v_add_u32_e32 v143, s63, v140
	ds_read_b128 v[160:163], v143
	ds_read_b128 v[178:181], v143 offset:1024
	ds_read_b128 v[182:185], v143 offset:2048
	ds_read_b128 v[186:189], v143 offset:3072
	s_add_i32 m0, s11, 0xc000
	ds_read_b128 v[206:209], v142
	ds_read_b128 v[210:213], v142 offset:1024
	ds_read_b128 v[214:217], v142 offset:2048
	ds_read_b128 v[218:221], v142 offset:3072
	ds_read_b128 v[222:225], v142 offset:4096
	ds_read_b128 v[226:229], v142 offset:5120
	ds_read_b128 v[230:233], v142 offset:6144
	ds_read_b128 v[234:237], v142 offset:7168
	global_load_lds_dwordx4 v136, s[66:67]
	s_add_i32 m0, s11, 0xe000
	s_nop 0
	global_load_lds_dwordx4 v138, s[66:67]
	s_waitcnt vmcnt(8)
	s_waitcnt lgkmcnt(0)
	s_barrier
	s_setprio 1
	s_waitcnt lgkmcnt(0)
	v_mfma_f32_16x16x32_bf16 v[126:129], v[144:147], v[206:209], v[126:129]
	v_mfma_f32_16x16x32_bf16 v[122:125], v[152:155], v[206:209], v[122:125]
	v_mfma_f32_16x16x32_bf16 v[118:121], v[144:147], v[214:217], v[118:121]
	v_mfma_f32_16x16x32_bf16 v[114:117], v[152:155], v[214:217], v[114:117]
	v_mfma_f32_16x16x32_bf16 v[102:105], v[144:147], v[222:225], v[102:105]
	v_mfma_f32_16x16x32_bf16 v[98:101], v[152:155], v[222:225], v[98:101]
	v_mfma_f32_16x16x32_bf16 v[86:89], v[144:147], v[230:233], v[86:89]
	v_mfma_f32_16x16x32_bf16 v[82:85], v[152:155], v[230:233], v[82:85]
	v_mfma_f32_16x16x32_bf16 v[126:129], v[148:151], v[210:213], v[126:129]
	v_mfma_f32_16x16x32_bf16 v[122:125], v[156:159], v[210:213], v[122:125]
	v_mfma_f32_16x16x32_bf16 v[118:121], v[148:151], v[218:221], v[118:121]
	v_mfma_f32_16x16x32_bf16 v[114:117], v[156:159], v[218:221], v[114:117]
	v_mfma_f32_16x16x32_bf16 v[102:105], v[148:151], v[226:229], v[102:105]
	v_mfma_f32_16x16x32_bf16 v[98:101], v[156:159], v[226:229], v[98:101]
	v_mfma_f32_16x16x32_bf16 v[86:89], v[148:151], v[234:237], v[86:89]
	v_mfma_f32_16x16x32_bf16 v[82:85], v[156:159], v[234:237], v[82:85]
	s_setprio 0
	s_setprio 1
	v_mfma_f32_16x16x32_bf16 v[110:113], v[160:163], v[206:209], v[110:113]
	v_mfma_f32_16x16x32_bf16 v[106:109], v[182:185], v[206:209], v[106:109]
	v_mfma_f32_16x16x32_bf16 v[94:97], v[160:163], v[214:217], v[94:97]
	v_mfma_f32_16x16x32_bf16 v[90:93], v[182:185], v[214:217], v[90:93]
	v_mfma_f32_16x16x32_bf16 v[78:81], v[160:163], v[222:225], v[78:81]
	v_mfma_f32_16x16x32_bf16 v[74:77], v[182:185], v[222:225], v[74:77]
	v_mfma_f32_16x16x32_bf16 v[70:73], v[160:163], v[230:233], v[70:73]
	v_mfma_f32_16x16x32_bf16 v[66:69], v[182:185], v[230:233], v[66:69]
	v_mfma_f32_16x16x32_bf16 v[110:113], v[178:181], v[210:213], v[110:113]
	v_mfma_f32_16x16x32_bf16 v[106:109], v[186:189], v[210:213], v[106:109]
	v_mfma_f32_16x16x32_bf16 v[94:97], v[178:181], v[218:221], v[94:97]
	v_mfma_f32_16x16x32_bf16 v[90:93], v[186:189], v[218:221], v[90:93]
	v_mfma_f32_16x16x32_bf16 v[78:81], v[178:181], v[226:229], v[78:81]
	v_mfma_f32_16x16x32_bf16 v[74:77], v[186:189], v[226:229], v[74:77]
	v_mfma_f32_16x16x32_bf16 v[70:73], v[178:181], v[234:237], v[70:73]
	v_mfma_f32_16x16x32_bf16 v[66:69], v[186:189], v[234:237], v[66:69]
	s_setprio 0
	s_barrier
	s_add_i32 s46, s62, s72
	s_mov_b32 m0, s46
	ds_read_b128 v[206:209], v142 offset:16384
	ds_read_b128 v[210:213], v142 offset:17408
	ds_read_b128 v[214:217], v142 offset:18432
	ds_read_b128 v[218:221], v142 offset:19456
	ds_read_b128 v[222:225], v142 offset:20480
	ds_read_b128 v[226:229], v142 offset:21504
	ds_read_b128 v[230:233], v142 offset:22528
	ds_read_b128 v[234:237], v142 offset:23552
	global_load_lds_dwordx4 v166, s[60:61]
	s_add_i32 m0, s46, 0x2000
	s_add_u32 s46, s60, 0x20000
	v_lshl_add_u64 v[242:243], s[60:61], 0, v[130:131]
	s_addc_u32 s47, s61, 0
	s_add_i32 s62, s63, s72
	global_load_lds_dwordx4 v130, s[60:61]
	s_mov_b32 m0, s62
	s_nop 0
	global_load_lds_dwordx4 v166, s[46:47]
	s_waitcnt vmcnt(5)
	s_waitcnt lgkmcnt(0)
	s_barrier
	s_setprio 1
	s_waitcnt lgkmcnt(0)
	v_mfma_f32_16x16x32_bf16 v[62:65], v[144:147], v[206:209], v[62:65]
	v_mfma_f32_16x16x32_bf16 v[58:61], v[152:155], v[206:209], v[58:61]
	v_mfma_f32_16x16x32_bf16 v[54:57], v[144:147], v[214:217], v[54:57]
	v_mfma_f32_16x16x32_bf16 v[50:53], v[152:155], v[214:217], v[50:53]
	v_mfma_f32_16x16x32_bf16 v[38:41], v[144:147], v[222:225], v[38:41]
	v_mfma_f32_16x16x32_bf16 v[34:37], v[152:155], v[222:225], v[34:37]
	s_add_i32 m0, s62, 0x2000
	s_nop 0
	global_load_lds_dwordx4 v130, s[46:47]
	v_mfma_f32_16x16x32_bf16 v[22:25], v[144:147], v[230:233], v[22:25]
	v_mfma_f32_16x16x32_bf16 v[18:21], v[152:155], v[230:233], v[18:21]
	v_mfma_f32_16x16x32_bf16 v[62:65], v[148:151], v[210:213], v[62:65]
	v_mfma_f32_16x16x32_bf16 v[58:61], v[156:159], v[210:213], v[58:61]
	v_mfma_f32_16x16x32_bf16 v[54:57], v[148:151], v[218:221], v[54:57]
	v_mfma_f32_16x16x32_bf16 v[50:53], v[156:159], v[218:221], v[50:53]
	v_mfma_f32_16x16x32_bf16 v[38:41], v[148:151], v[226:229], v[38:41]
	v_mfma_f32_16x16x32_bf16 v[34:37], v[156:159], v[226:229], v[34:37]
	v_mfma_f32_16x16x32_bf16 v[22:25], v[148:151], v[234:237], v[22:25]
	v_mfma_f32_16x16x32_bf16 v[18:21], v[156:159], v[234:237], v[18:21]
	s_mov_b32 m0, s11
	s_nop 0
	global_load_lds_dwordx4 v134, s[68:69]
	s_setprio 0
	s_setprio 1
	v_mfma_f32_16x16x32_bf16 v[46:49], v[160:163], v[206:209], v[46:49]
	v_mfma_f32_16x16x32_bf16 v[42:45], v[182:185], v[206:209], v[42:45]
	v_mfma_f32_16x16x32_bf16 v[30:33], v[160:163], v[214:217], v[30:33]
	v_mfma_f32_16x16x32_bf16 v[26:29], v[182:185], v[214:217], v[26:29]
	v_mfma_f32_16x16x32_bf16 v[14:17], v[160:163], v[222:225], v[14:17]
	v_mfma_f32_16x16x32_bf16 v[10:13], v[182:185], v[222:225], v[10:13]
	v_mfma_f32_16x16x32_bf16 v[6:9], v[160:163], v[230:233], v[6:9]
	v_mfma_f32_16x16x32_bf16 v[2:5], v[182:185], v[230:233], v[2:5]
	v_mfma_f32_16x16x32_bf16 v[46:49], v[178:181], v[210:213], v[46:49]
	v_mfma_f32_16x16x32_bf16 v[42:45], v[186:189], v[210:213], v[42:45]
	s_mov_b32 m0, s74
	s_nop 0
	global_load_lds_dwordx4 v132, s[68:69]
	v_mfma_f32_16x16x32_bf16 v[30:33], v[178:181], v[218:221], v[30:33]
	v_mfma_f32_16x16x32_bf16 v[26:29], v[186:189], v[218:221], v[26:29]
	v_mfma_f32_16x16x32_bf16 v[14:17], v[178:181], v[226:229], v[14:17]
	v_mfma_f32_16x16x32_bf16 v[10:13], v[186:189], v[226:229], v[10:13]
	v_mfma_f32_16x16x32_bf16 v[6:9], v[178:181], v[234:237], v[6:9]
	v_mfma_f32_16x16x32_bf16 v[2:5], v[186:189], v[234:237], v[2:5]
	s_setprio 0
	s_barrier
	s_add_i32 s62, 0, 0x18000
	v_add_u32_e32 v143, s62, v140
	s_add_i32 s63, 0, 0x1c000
	ds_read_b128 v[144:147], v143
	ds_read_b128 v[148:151], v143 offset:1024
	ds_read_b128 v[152:155], v143 offset:2048
	ds_read_b128 v[156:159], v143 offset:3072
	v_add_u32_e32 v143, s63, v140
	ds_read_b128 v[160:163], v143
	ds_read_b128 v[178:181], v143 offset:1024
	ds_read_b128 v[182:185], v143 offset:2048
	ds_read_b128 v[186:189], v143 offset:3072
	s_add_u32 s46, s68, 0x20000
	s_addc_u32 s47, s69, 0
	s_mov_b32 m0, s75
	ds_read_b128 v[206:209], v142 offset:32768
	ds_read_b128 v[210:213], v142 offset:33792
	ds_read_b128 v[214:217], v142 offset:34816
	ds_read_b128 v[218:221], v142 offset:35840
	ds_read_b128 v[222:225], v142 offset:36864
	ds_read_b128 v[226:229], v142 offset:37888
	ds_read_b128 v[230:233], v142 offset:38912
	ds_read_b128 v[234:237], v142 offset:39936
	global_load_lds_dwordx4 v134, s[46:47]
	s_mov_b32 m0, s76
	s_nop 0
	global_load_lds_dwordx4 v132, s[46:47]
	s_waitcnt vmcnt(8)
	s_waitcnt lgkmcnt(0)
	s_barrier
	s_setprio 1
	s_waitcnt lgkmcnt(0)
	v_mfma_f32_16x16x32_bf16 v[126:129], v[144:147], v[206:209], v[126:129]
	v_mfma_f32_16x16x32_bf16 v[122:125], v[152:155], v[206:209], v[122:125]
	v_mfma_f32_16x16x32_bf16 v[118:121], v[144:147], v[214:217], v[118:121]
	v_mfma_f32_16x16x32_bf16 v[114:117], v[152:155], v[214:217], v[114:117]
	v_mfma_f32_16x16x32_bf16 v[102:105], v[144:147], v[222:225], v[102:105]
	v_mfma_f32_16x16x32_bf16 v[98:101], v[152:155], v[222:225], v[98:101]
	v_mfma_f32_16x16x32_bf16 v[86:89], v[144:147], v[230:233], v[86:89]
	v_mfma_f32_16x16x32_bf16 v[82:85], v[152:155], v[230:233], v[82:85]
	v_mfma_f32_16x16x32_bf16 v[126:129], v[148:151], v[210:213], v[126:129]
	v_mfma_f32_16x16x32_bf16 v[122:125], v[156:159], v[210:213], v[122:125]
	v_mfma_f32_16x16x32_bf16 v[118:121], v[148:151], v[218:221], v[118:121]
	v_mfma_f32_16x16x32_bf16 v[114:117], v[156:159], v[218:221], v[114:117]
	v_mfma_f32_16x16x32_bf16 v[102:105], v[148:151], v[226:229], v[102:105]
	v_mfma_f32_16x16x32_bf16 v[98:101], v[156:159], v[226:229], v[98:101]
	v_mfma_f32_16x16x32_bf16 v[86:89], v[148:151], v[234:237], v[86:89]
	v_mfma_f32_16x16x32_bf16 v[82:85], v[156:159], v[234:237], v[82:85]
	s_setprio 0
	s_setprio 1
	v_mfma_f32_16x16x32_bf16 v[110:113], v[160:163], v[206:209], v[110:113]
	v_mfma_f32_16x16x32_bf16 v[106:109], v[182:185], v[206:209], v[106:109]
	v_mfma_f32_16x16x32_bf16 v[94:97], v[160:163], v[214:217], v[94:97]
	v_mfma_f32_16x16x32_bf16 v[90:93], v[182:185], v[214:217], v[90:93]
	v_mfma_f32_16x16x32_bf16 v[78:81], v[160:163], v[222:225], v[78:81]
	v_mfma_f32_16x16x32_bf16 v[74:77], v[182:185], v[222:225], v[74:77]
	v_mfma_f32_16x16x32_bf16 v[70:73], v[160:163], v[230:233], v[70:73]
	v_mfma_f32_16x16x32_bf16 v[66:69], v[182:185], v[230:233], v[66:69]
	v_mfma_f32_16x16x32_bf16 v[110:113], v[178:181], v[210:213], v[110:113]
	v_mfma_f32_16x16x32_bf16 v[106:109], v[186:189], v[210:213], v[106:109]
	v_mfma_f32_16x16x32_bf16 v[94:97], v[178:181], v[218:221], v[94:97]
	v_mfma_f32_16x16x32_bf16 v[90:93], v[186:189], v[218:221], v[90:93]
	v_mfma_f32_16x16x32_bf16 v[78:81], v[178:181], v[226:229], v[78:81]
	v_mfma_f32_16x16x32_bf16 v[74:77], v[186:189], v[226:229], v[74:77]
	v_mfma_f32_16x16x32_bf16 v[70:73], v[178:181], v[234:237], v[70:73]
	v_mfma_f32_16x16x32_bf16 v[66:69], v[186:189], v[234:237], v[66:69]
	s_setprio 0
	s_barrier
	s_add_i32 s46, s62, s72
	s_mov_b32 m0, s46
	ds_read_b128 v[206:209], v142 offset:49152
	ds_read_b128 v[210:213], v142 offset:50176
	ds_read_b128 v[214:217], v142 offset:51200
	ds_read_b128 v[218:221], v142 offset:52224
	ds_read_b128 v[222:225], v142 offset:53248
	ds_read_b128 v[226:229], v142 offset:54272
	ds_read_b128 v[230:233], v142 offset:55296
	ds_read_b128 v[234:237], v142 offset:56320
	s_add_u32 s100, s60, 128
	s_addc_u32 s101, s61, 0
	global_load_lds_dwordx4 v166, s[100:101]
	s_add_i32 m0, s46, 0x2000
	s_add_u32 s46, s60, 0x20080
	v_lshl_add_u64 v[164:165], v[242:243], 0, s[42:43]
	s_addc_u32 s47, s61, 0
	s_add_i32 s60, s63, s72
	global_load_lds_dwordx4 v[164:165], off
	s_mov_b32 m0, s60
	s_nop 0
	global_load_lds_dwordx4 v166, s[46:47]
	s_waitcnt vmcnt(5)
	s_waitcnt lgkmcnt(0)
	s_barrier
	s_setprio 1
	s_waitcnt lgkmcnt(0)
	v_mfma_f32_16x16x32_bf16 v[62:65], v[144:147], v[206:209], v[62:65]
	v_mfma_f32_16x16x32_bf16 v[58:61], v[152:155], v[206:209], v[58:61]
	v_mfma_f32_16x16x32_bf16 v[54:57], v[144:147], v[214:217], v[54:57]
	v_mfma_f32_16x16x32_bf16 v[50:53], v[152:155], v[214:217], v[50:53]
	v_mfma_f32_16x16x32_bf16 v[38:41], v[144:147], v[222:225], v[38:41]
	v_mfma_f32_16x16x32_bf16 v[34:37], v[152:155], v[222:225], v[34:37]
	s_add_i32 m0, s60, 0x2000
	s_nop 0
	global_load_lds_dwordx4 v130, s[46:47]
	v_mfma_f32_16x16x32_bf16 v[22:25], v[144:147], v[230:233], v[22:25]
	v_mfma_f32_16x16x32_bf16 v[18:21], v[152:155], v[230:233], v[18:21]
	v_mfma_f32_16x16x32_bf16 v[62:65], v[148:151], v[210:213], v[62:65]
	v_mfma_f32_16x16x32_bf16 v[58:61], v[156:159], v[210:213], v[58:61]
	v_mfma_f32_16x16x32_bf16 v[54:57], v[148:151], v[218:221], v[54:57]
	v_mfma_f32_16x16x32_bf16 v[50:53], v[156:159], v[218:221], v[50:53]
	v_mfma_f32_16x16x32_bf16 v[38:41], v[148:151], v[226:229], v[38:41]
	v_mfma_f32_16x16x32_bf16 v[34:37], v[156:159], v[226:229], v[34:37]
	v_mfma_f32_16x16x32_bf16 v[22:25], v[148:151], v[234:237], v[22:25]
	v_mfma_f32_16x16x32_bf16 v[18:21], v[156:159], v[234:237], v[18:21]
	s_mov_b32 m0, s77
	s_nop 0
	s_add_u32 s100, s68, 128
	s_addc_u32 s101, s69, 0
	global_load_lds_dwordx4 v134, s[100:101]
	s_setprio 0
	s_setprio 1
	v_mfma_f32_16x16x32_bf16 v[46:49], v[160:163], v[206:209], v[46:49]
	v_mfma_f32_16x16x32_bf16 v[42:45], v[182:185], v[206:209], v[42:45]
	v_mfma_f32_16x16x32_bf16 v[30:33], v[160:163], v[214:217], v[30:33]
	v_mfma_f32_16x16x32_bf16 v[26:29], v[182:185], v[214:217], v[26:29]
	v_mfma_f32_16x16x32_bf16 v[14:17], v[160:163], v[222:225], v[14:17]
	v_mfma_f32_16x16x32_bf16 v[10:13], v[182:185], v[222:225], v[10:13]
	v_mfma_f32_16x16x32_bf16 v[6:9], v[160:163], v[230:233], v[6:9]
	v_mfma_f32_16x16x32_bf16 v[2:5], v[182:185], v[230:233], v[2:5]
	v_mfma_f32_16x16x32_bf16 v[46:49], v[178:181], v[210:213], v[46:49]
	v_mfma_f32_16x16x32_bf16 v[42:45], v[186:189], v[210:213], v[42:45]
	s_mov_b32 m0, s78
	s_nop 0
	s_add_u32 s100, s68, 128
	s_addc_u32 s101, s69, 0
	global_load_lds_dwordx4 v132, s[100:101]
	v_mfma_f32_16x16x32_bf16 v[30:33], v[178:181], v[218:221], v[30:33]
	v_mfma_f32_16x16x32_bf16 v[26:29], v[186:189], v[218:221], v[26:29]
	v_mfma_f32_16x16x32_bf16 v[14:17], v[178:181], v[226:229], v[14:17]
	v_mfma_f32_16x16x32_bf16 v[10:13], v[186:189], v[226:229], v[10:13]
	v_mfma_f32_16x16x32_bf16 v[6:9], v[178:181], v[234:237], v[6:9]
	v_mfma_f32_16x16x32_bf16 v[2:5], v[186:189], v[234:237], v[2:5]
	s_setprio 0
	s_barrier
	s_add_i32 s84, s84, 2
	s_add_u32 s66, s66, 0x100
	s_addc_u32 s67, s67, 0
	s_add_u32 s82, s82, 0x100
	s_addc_u32 s83, s83, 0
	s_cmp_gt_u32 s84, 5
	s_cbranch_scc0 .LBB0_426
	s_and_b64 vcc, exec, s[12:13]
	s_cbranch_vccz .LBB0_429
	s_barrier

.LBB0_442:
	s_add_u32 s62, s18, s72
	s_addc_u32 s63, s19, 0
	s_add_u32 s73, s62, 0x100
	s_addc_u32 s74, s63, 0
	s_and_b64 s[46:47], s[60:61], exec
	s_cselect_b32 s75, s23, s74
	s_cselect_b32 s74, s92, s73
	s_add_u32 s46, s16, s72
	s_addc_u32 s47, s17, 0
	s_add_u32 s72, s46, 0x100
	s_addc_u32 s73, s47, 0
	s_add_i32 s48, 0, 0x10000
	s_and_b64 s[46:47], s[60:61], exec
	s_cselect_b32 s77, s21, s73
	s_cselect_b32 s76, s93, s72
	s_add_i32 s46, 0, 0x14000
	s_add_u32 s80, s62, 0x10080
	s_addc_u32 s81, s63, 0
	s_add_i32 s63, s48, s84
	s_add_i32 m0, s13, 0xc000
	s_add_i32 s49, s13, 0xe000
	s_add_i32 vcc_lo, s63, 0x2000
	v_add_u32_e32 v139, s48, v136
	s_add_u32 s78, s76, 0x10000
	ds_read_b128 v[140:143], v139
	ds_read_b128 v[144:147], v139 offset:1024
	ds_read_b128 v[148:151], v139 offset:2048
	ds_read_b128 v[152:155], v139 offset:3072
	v_add_u32_e32 v139, s46, v136
	s_addc_u32 s79, s77, 0
	s_add_i32 vcc_hi, s46, s84
	ds_read_b128 v[156:159], v139
	ds_read_b128 v[160:163], v139 offset:1024
	ds_read_b128 v[178:181], v139 offset:2048
	ds_read_b128 v[182:185], v139 offset:3072
	s_add_i32 s62, vcc_hi, 0x2000
	s_add_i32 s97, 0, 0x18000
	s_add_i32 s96, 0, 0x1c000
	s_add_u32 s72, s74, 0x10000
	s_addc_u32 s73, s75, 0
	s_add_i32 s95, s97, s84
	s_add_i32 s94, s95, 0x2000
	s_add_u32 s60, s76, 0x10080
	s_addc_u32 s61, s77, 0
	s_add_i32 s47, s96, s84
	s_add_i32 s46, s47, 0x2000
	ds_read_b128 v[186:189], v138
	ds_read_b128 v[206:209], v138 offset:1024
	ds_read_b128 v[210:213], v138 offset:2048
	ds_read_b128 v[214:217], v138 offset:3072
	ds_read_b128 v[218:221], v138 offset:4096
	ds_read_b128 v[222:225], v138 offset:5120
	ds_read_b128 v[226:229], v138 offset:6144
	ds_read_b128 v[230:233], v138 offset:7168
	global_load_lds_dwordx4 v134, s[80:81]
	s_mov_b32 m0, s49
	s_nop 0
	global_load_lds_dwordx4 v132, s[80:81]
	s_waitcnt vmcnt(8)
	s_waitcnt lgkmcnt(0)
	s_barrier
	s_setprio 1
	s_waitcnt lgkmcnt(0)
	v_mfma_f32_16x16x32_bf16 v[126:129], v[140:143], v[186:189], v[126:129]
	v_mfma_f32_16x16x32_bf16 v[122:125], v[148:151], v[186:189], v[122:125]
	v_mfma_f32_16x16x32_bf16 v[118:121], v[140:143], v[210:213], v[118:121]
	v_mfma_f32_16x16x32_bf16 v[114:117], v[148:151], v[210:213], v[114:117]
	v_mfma_f32_16x16x32_bf16 v[102:105], v[140:143], v[218:221], v[102:105]
	v_mfma_f32_16x16x32_bf16 v[98:101], v[148:151], v[218:221], v[98:101]
	v_mfma_f32_16x16x32_bf16 v[86:89], v[140:143], v[226:229], v[86:89]
	v_mfma_f32_16x16x32_bf16 v[82:85], v[148:151], v[226:229], v[82:85]
	v_mfma_f32_16x16x32_bf16 v[126:129], v[144:147], v[206:209], v[126:129]
	v_mfma_f32_16x16x32_bf16 v[122:125], v[152:155], v[206:209], v[122:125]
	v_mfma_f32_16x16x32_bf16 v[118:121], v[144:147], v[214:217], v[118:121]
	v_mfma_f32_16x16x32_bf16 v[114:117], v[152:155], v[214:217], v[114:117]
	v_mfma_f32_16x16x32_bf16 v[102:105], v[144:147], v[222:225], v[102:105]
	v_mfma_f32_16x16x32_bf16 v[98:101], v[152:155], v[222:225], v[98:101]
	v_mfma_f32_16x16x32_bf16 v[86:89], v[144:147], v[230:233], v[86:89]
	v_mfma_f32_16x16x32_bf16 v[82:85], v[152:155], v[230:233], v[82:85]
	s_setprio 0
	s_setprio 1
	v_mfma_f32_16x16x32_bf16 v[110:113], v[156:159], v[186:189], v[110:113]
	v_mfma_f32_16x16x32_bf16 v[106:109], v[178:181], v[186:189], v[106:109]
	v_mfma_f32_16x16x32_bf16 v[94:97], v[156:159], v[210:213], v[94:97]
	v_mfma_f32_16x16x32_bf16 v[90:93], v[178:181], v[210:213], v[90:93]
	v_mfma_f32_16x16x32_bf16 v[78:81], v[156:159], v[218:221], v[78:81]
	v_mfma_f32_16x16x32_bf16 v[74:77], v[178:181], v[218:221], v[74:77]
	v_mfma_f32_16x16x32_bf16 v[70:73], v[156:159], v[226:229], v[70:73]
	v_mfma_f32_16x16x32_bf16 v[66:69], v[178:181], v[226:229], v[66:69]
	v_mfma_f32_16x16x32_bf16 v[110:113], v[160:163], v[206:209], v[110:113]
	v_mfma_f32_16x16x32_bf16 v[106:109], v[182:185], v[206:209], v[106:109]
	v_mfma_f32_16x16x32_bf16 v[94:97], v[160:163], v[214:217], v[94:97]
	v_mfma_f32_16x16x32_bf16 v[90:93], v[182:185], v[214:217], v[90:93]
	v_mfma_f32_16x16x32_bf16 v[78:81], v[160:163], v[222:225], v[78:81]
	v_mfma_f32_16x16x32_bf16 v[74:77], v[182:185], v[222:225], v[74:77]
	v_mfma_f32_16x16x32_bf16 v[70:73], v[160:163], v[230:233], v[70:73]
	v_mfma_f32_16x16x32_bf16 v[66:69], v[182:185], v[230:233], v[66:69]
	s_setprio 0
	s_barrier
	s_mov_b32 m0, s63
	ds_read_b128 v[186:189], v138 offset:16384
	ds_read_b128 v[206:209], v138 offset:17408
	ds_read_b128 v[210:213], v138 offset:18432
	ds_read_b128 v[214:217], v138 offset:19456
	ds_read_b128 v[218:221], v138 offset:20480
	ds_read_b128 v[222:225], v138 offset:21504
	ds_read_b128 v[226:229], v138 offset:22528
	ds_read_b128 v[230:233], v138 offset:23552
	global_load_lds_dwordx4 v166, s[76:77]
	s_mov_b32 m0, vcc_lo
	s_nop 0
	global_load_lds_dwordx4 v130, s[76:77]
	s_mov_b32 m0, vcc_hi
	s_nop 0
	global_load_lds_dwordx4 v166, s[78:79]
	s_waitcnt vmcnt(5)
	s_waitcnt lgkmcnt(0)
	s_barrier
	s_setprio 1
	s_waitcnt lgkmcnt(0)
	v_mfma_f32_16x16x32_bf16 v[62:65], v[140:143], v[186:189], v[62:65]
	v_mfma_f32_16x16x32_bf16 v[58:61], v[148:151], v[186:189], v[58:61]
	v_mfma_f32_16x16x32_bf16 v[54:57], v[140:143], v[210:213], v[54:57]
	v_mfma_f32_16x16x32_bf16 v[50:53], v[148:151], v[210:213], v[50:53]
	v_mfma_f32_16x16x32_bf16 v[38:41], v[140:143], v[218:221], v[38:41]
	v_mfma_f32_16x16x32_bf16 v[34:37], v[148:151], v[218:221], v[34:37]
	s_mov_b32 m0, s62
	s_nop 0
	global_load_lds_dwordx4 v130, s[78:79]
	v_mfma_f32_16x16x32_bf16 v[22:25], v[140:143], v[226:229], v[22:25]
	v_mfma_f32_16x16x32_bf16 v[18:21], v[148:151], v[226:229], v[18:21]
	v_mfma_f32_16x16x32_bf16 v[62:65], v[144:147], v[206:209], v[62:65]
	v_mfma_f32_16x16x32_bf16 v[58:61], v[152:155], v[206:209], v[58:61]
	v_mfma_f32_16x16x32_bf16 v[54:57], v[144:147], v[214:217], v[54:57]
	v_mfma_f32_16x16x32_bf16 v[50:53], v[152:155], v[214:217], v[50:53]
	v_mfma_f32_16x16x32_bf16 v[38:41], v[144:147], v[222:225], v[38:41]
	v_mfma_f32_16x16x32_bf16 v[34:37], v[152:155], v[222:225], v[34:37]
	v_mfma_f32_16x16x32_bf16 v[22:25], v[144:147], v[230:233], v[22:25]
	v_mfma_f32_16x16x32_bf16 v[18:21], v[152:155], v[230:233], v[18:21]
	s_mov_b32 m0, s13
	s_nop 0
	global_load_lds_dwordx4 v134, s[74:75]
	s_setprio 0
	s_setprio 1
	v_mfma_f32_16x16x32_bf16 v[46:49], v[156:159], v[186:189], v[46:49]
	v_mfma_f32_16x16x32_bf16 v[42:45], v[178:181], v[186:189], v[42:45]
	v_mfma_f32_16x16x32_bf16 v[30:33], v[156:159], v[210:213], v[30:33]
	v_mfma_f32_16x16x32_bf16 v[26:29], v[178:181], v[210:213], v[26:29]
	v_mfma_f32_16x16x32_bf16 v[14:17], v[156:159], v[218:221], v[14:17]
	v_mfma_f32_16x16x32_bf16 v[10:13], v[178:181], v[218:221], v[10:13]
	v_mfma_f32_16x16x32_bf16 v[6:9], v[156:159], v[226:229], v[6:9]
	v_mfma_f32_16x16x32_bf16 v[2:5], v[178:181], v[226:229], v[2:5]
	v_mfma_f32_16x16x32_bf16 v[46:49], v[160:163], v[206:209], v[46:49]
	v_mfma_f32_16x16x32_bf16 v[42:45], v[182:185], v[206:209], v[42:45]
	s_mov_b32 m0, s86
	s_nop 0
	global_load_lds_dwordx4 v132, s[74:75]
	v_mfma_f32_16x16x32_bf16 v[30:33], v[160:163], v[214:217], v[30:33]
	v_mfma_f32_16x16x32_bf16 v[26:29], v[182:185], v[214:217], v[26:29]
	v_mfma_f32_16x16x32_bf16 v[14:17], v[160:163], v[222:225], v[14:17]
	v_mfma_f32_16x16x32_bf16 v[10:13], v[182:185], v[222:225], v[10:13]
	v_mfma_f32_16x16x32_bf16 v[6:9], v[160:163], v[230:233], v[6:9]
	v_mfma_f32_16x16x32_bf16 v[2:5], v[182:185], v[230:233], v[2:5]
	s_setprio 0
	s_barrier
	v_add_u32_e32 v139, s97, v136
	ds_read_b128 v[140:143], v139
	ds_read_b128 v[144:147], v139 offset:1024
	ds_read_b128 v[148:151], v139 offset:2048
	ds_read_b128 v[152:155], v139 offset:3072
	v_add_u32_e32 v139, s96, v136
	ds_read_b128 v[156:159], v139
	ds_read_b128 v[160:163], v139 offset:1024
	ds_read_b128 v[178:181], v139 offset:2048
	ds_read_b128 v[182:185], v139 offset:3072
	s_mov_b32 m0, s87
	ds_read_b128 v[186:189], v138 offset:32768
	ds_read_b128 v[206:209], v138 offset:33792
	ds_read_b128 v[210:213], v138 offset:34816
	ds_read_b128 v[214:217], v138 offset:35840
	ds_read_b128 v[218:221], v138 offset:36864
	ds_read_b128 v[222:225], v138 offset:37888
	ds_read_b128 v[226:229], v138 offset:38912
	ds_read_b128 v[230:233], v138 offset:39936
	global_load_lds_dwordx4 v134, s[72:73]
	s_mov_b32 m0, s88
	s_nop 0
	global_load_lds_dwordx4 v132, s[72:73]
	s_waitcnt vmcnt(8)
	s_waitcnt lgkmcnt(0)
	s_barrier
	s_setprio 1
	s_waitcnt lgkmcnt(0)
	v_mfma_f32_16x16x32_bf16 v[126:129], v[140:143], v[186:189], v[126:129]
	v_mfma_f32_16x16x32_bf16 v[122:125], v[148:151], v[186:189], v[122:125]
	v_mfma_f32_16x16x32_bf16 v[118:121], v[140:143], v[210:213], v[118:121]
	v_mfma_f32_16x16x32_bf16 v[114:117], v[148:151], v[210:213], v[114:117]
	v_mfma_f32_16x16x32_bf16 v[102:105], v[140:143], v[218:221], v[102:105]
	v_mfma_f32_16x16x32_bf16 v[98:101], v[148:151], v[218:221], v[98:101]
	v_mfma_f32_16x16x32_bf16 v[86:89], v[140:143], v[226:229], v[86:89]
	v_mfma_f32_16x16x32_bf16 v[82:85], v[148:151], v[226:229], v[82:85]
	v_mfma_f32_16x16x32_bf16 v[126:129], v[144:147], v[206:209], v[126:129]
	v_mfma_f32_16x16x32_bf16 v[122:125], v[152:155], v[206:209], v[122:125]
	v_mfma_f32_16x16x32_bf16 v[118:121], v[144:147], v[214:217], v[118:121]
	v_mfma_f32_16x16x32_bf16 v[114:117], v[152:155], v[214:217], v[114:117]
	v_mfma_f32_16x16x32_bf16 v[102:105], v[144:147], v[222:225], v[102:105]
	v_mfma_f32_16x16x32_bf16 v[98:101], v[152:155], v[222:225], v[98:101]
	v_mfma_f32_16x16x32_bf16 v[86:89], v[144:147], v[230:233], v[86:89]
	v_mfma_f32_16x16x32_bf16 v[82:85], v[152:155], v[230:233], v[82:85]
	s_setprio 0
	s_setprio 1
	v_mfma_f32_16x16x32_bf16 v[110:113], v[156:159], v[186:189], v[110:113]
	v_mfma_f32_16x16x32_bf16 v[106:109], v[178:181], v[186:189], v[106:109]
	v_mfma_f32_16x16x32_bf16 v[94:97], v[156:159], v[210:213], v[94:97]
	v_mfma_f32_16x16x32_bf16 v[90:93], v[178:181], v[210:213], v[90:93]
	v_mfma_f32_16x16x32_bf16 v[78:81], v[156:159], v[218:221], v[78:81]
	v_mfma_f32_16x16x32_bf16 v[74:77], v[178:181], v[218:221], v[74:77]
	v_mfma_f32_16x16x32_bf16 v[70:73], v[156:159], v[226:229], v[70:73]
	v_mfma_f32_16x16x32_bf16 v[66:69], v[178:181], v[226:229], v[66:69]
	v_mfma_f32_16x16x32_bf16 v[110:113], v[160:163], v[206:209], v[110:113]
	v_mfma_f32_16x16x32_bf16 v[106:109], v[182:185], v[206:209], v[106:109]
	v_mfma_f32_16x16x32_bf16 v[94:97], v[160:163], v[214:217], v[94:97]
	v_mfma_f32_16x16x32_bf16 v[90:93], v[182:185], v[214:217], v[90:93]
	v_mfma_f32_16x16x32_bf16 v[78:81], v[160:163], v[222:225], v[78:81]
	v_mfma_f32_16x16x32_bf16 v[74:77], v[182:185], v[222:225], v[74:77]
	v_mfma_f32_16x16x32_bf16 v[70:73], v[160:163], v[230:233], v[70:73]
	v_mfma_f32_16x16x32_bf16 v[66:69], v[182:185], v[230:233], v[66:69]
	s_setprio 0
	s_barrier
	s_mov_b32 m0, s95
	ds_read_b128 v[186:189], v138 offset:49152
	ds_read_b128 v[206:209], v138 offset:50176
	ds_read_b128 v[210:213], v138 offset:51200
	ds_read_b128 v[214:217], v138 offset:52224
	ds_read_b128 v[218:221], v138 offset:53248
	ds_read_b128 v[222:225], v138 offset:54272
	ds_read_b128 v[226:229], v138 offset:55296
	ds_read_b128 v[230:233], v138 offset:56320
	s_add_u32 s100, s76, 128
	s_addc_u32 s101, s77, 0
	global_load_lds_dwordx4 v166, s[100:101]
	s_mov_b32 m0, s94
	s_nop 0
	s_add_u32 s100, s76, 128
	s_addc_u32 s101, s77, 0
	global_load_lds_dwordx4 v130, s[100:101]
	s_mov_b32 m0, s47
	s_nop 0
	global_load_lds_dwordx4 v166, s[60:61]
	s_waitcnt vmcnt(5)
	s_waitcnt lgkmcnt(0)
	s_barrier
	s_setprio 1
	s_waitcnt lgkmcnt(0)
	v_mfma_f32_16x16x32_bf16 v[62:65], v[140:143], v[186:189], v[62:65]
	v_mfma_f32_16x16x32_bf16 v[58:61], v[148:151], v[186:189], v[58:61]
	v_mfma_f32_16x16x32_bf16 v[54:57], v[140:143], v[210:213], v[54:57]
	v_mfma_f32_16x16x32_bf16 v[50:53], v[148:151], v[210:213], v[50:53]
	v_mfma_f32_16x16x32_bf16 v[38:41], v[140:143], v[218:221], v[38:41]
	v_mfma_f32_16x16x32_bf16 v[34:37], v[148:151], v[218:221], v[34:37]
	s_mov_b32 m0, s46
	s_nop 0
	global_load_lds_dwordx4 v130, s[60:61]
	v_mfma_f32_16x16x32_bf16 v[22:25], v[140:143], v[226:229], v[22:25]
	v_mfma_f32_16x16x32_bf16 v[18:21], v[148:151], v[226:229], v[18:21]
	v_mfma_f32_16x16x32_bf16 v[62:65], v[144:147], v[206:209], v[62:65]
	v_mfma_f32_16x16x32_bf16 v[58:61], v[152:155], v[206:209], v[58:61]
	v_mfma_f32_16x16x32_bf16 v[54:57], v[144:147], v[214:217], v[54:57]
	v_mfma_f32_16x16x32_bf16 v[50:53], v[152:155], v[214:217], v[50:53]
	v_mfma_f32_16x16x32_bf16 v[38:41], v[144:147], v[222:225], v[38:41]
	v_mfma_f32_16x16x32_bf16 v[34:37], v[152:155], v[222:225], v[34:37]
	v_mfma_f32_16x16x32_bf16 v[22:25], v[144:147], v[230:233], v[22:25]
	v_mfma_f32_16x16x32_bf16 v[18:21], v[152:155], v[230:233], v[18:21]
	s_mov_b32 m0, s89
	s_nop 0
	s_add_u32 s100, s74, 128
	s_addc_u32 s101, s75, 0
	global_load_lds_dwordx4 v134, s[100:101]
	s_setprio 0
	s_setprio 1
	v_mfma_f32_16x16x32_bf16 v[46:49], v[156:159], v[186:189], v[46:49]
	v_mfma_f32_16x16x32_bf16 v[42:45], v[178:181], v[186:189], v[42:45]
	v_mfma_f32_16x16x32_bf16 v[30:33], v[156:159], v[210:213], v[30:33]
	v_mfma_f32_16x16x32_bf16 v[26:29], v[178:181], v[210:213], v[26:29]
	v_mfma_f32_16x16x32_bf16 v[14:17], v[156:159], v[218:221], v[14:17]
	v_mfma_f32_16x16x32_bf16 v[10:13], v[178:181], v[218:221], v[10:13]
	v_mfma_f32_16x16x32_bf16 v[6:9], v[156:159], v[226:229], v[6:9]
	v_mfma_f32_16x16x32_bf16 v[2:5], v[178:181], v[226:229], v[2:5]
	v_mfma_f32_16x16x32_bf16 v[46:49], v[160:163], v[206:209], v[46:49]
	v_mfma_f32_16x16x32_bf16 v[42:45], v[182:185], v[206:209], v[42:45]
	s_mov_b32 m0, s90
	s_nop 0
	s_add_u32 s100, s74, 128
	s_addc_u32 s101, s75, 0
	global_load_lds_dwordx4 v132, s[100:101]
	v_mfma_f32_16x16x32_bf16 v[30:33], v[160:163], v[214:217], v[30:33]
	v_mfma_f32_16x16x32_bf16 v[26:29], v[182:185], v[214:217], v[26:29]
	v_mfma_f32_16x16x32_bf16 v[14:17], v[160:163], v[222:225], v[14:17]
	v_mfma_f32_16x16x32_bf16 v[10:13], v[182:185], v[222:225], v[10:13]
	v_mfma_f32_16x16x32_bf16 v[6:9], v[160:163], v[230:233], v[6:9]
	v_mfma_f32_16x16x32_bf16 v[2:5], v[182:185], v[230:233], v[2:5]
	s_setprio 0
	s_barrier
	s_movk_i32 s72, 0x100
	s_andn2_b64 vcc, exec, s[70:71]
	s_mov_b64 s[60:61], -1
	s_mov_b64 s[70:71], 0
	s_cbranch_vccz .LBB0_442
	s_and_b64 vcc, exec, s[10:11]
	s_cbranch_vccz .LBB0_445
	s_barrier

.LBB0_795:
	s_add_u32 s46, s68, 0xfff80080
	s_addc_u32 s47, s69, -1
	s_add_i32 s48, 0, 0x10000
	s_cmp_eq_u32 s87, 28
	s_cselect_b32 s71, s19, s47
	s_cselect_b32 s70, s83, s46
	s_cselect_b32 s61, s17, s86
	s_cselect_b32 s60, s84, s85
	s_add_i32 s49, 0, 0x14000
	v_add_u32_e32 v156, s48, v1
	v_add_u32_e32 v164, s49, v1
	ds_read_b128 v[130:133], v156
	ds_read_b128 v[134:137], v156 offset:1024
	ds_read_b128 v[150:153], v156 offset:2048
	ds_read_b128 v[156:159], v156 offset:3072
	ds_read_b128 v[160:163], v164
	ds_read_b128 v[178:181], v164 offset:1024
	ds_read_b128 v[182:185], v164 offset:2048
	ds_read_b128 v[186:189], v164 offset:3072
	s_add_i32 m0, s67, 0xc000
	ds_read_b128 v[206:209], v155
	ds_read_b128 v[210:213], v155 offset:1024
	ds_read_b128 v[214:217], v155 offset:2048
	ds_read_b128 v[218:221], v155 offset:3072
	ds_read_b128 v[222:225], v155 offset:4096
	ds_read_b128 v[226:229], v155 offset:5120
	ds_read_b128 v[230:233], v155 offset:6144
	ds_read_b128 v[234:237], v155 offset:7168
	global_load_lds_dwordx4 v146, s[68:69]
	s_add_i32 m0, s67, 0xe000
	s_nop 0
	global_load_lds_dwordx4 v148, s[68:69]
	s_waitcnt vmcnt(8)
	s_waitcnt lgkmcnt(0)
	s_barrier
	s_setprio 1
	s_waitcnt lgkmcnt(0)
	v_mfma_f32_16x16x32_bf16 v[126:129], v[130:133], v[206:209], v[126:129]
	v_mfma_f32_16x16x32_bf16 v[122:125], v[150:153], v[206:209], v[122:125]
	v_mfma_f32_16x16x32_bf16 v[118:121], v[130:133], v[214:217], v[118:121]
	v_mfma_f32_16x16x32_bf16 v[114:117], v[150:153], v[214:217], v[114:117]
	v_mfma_f32_16x16x32_bf16 v[110:113], v[130:133], v[222:225], v[110:113]
	v_mfma_f32_16x16x32_bf16 v[106:109], v[150:153], v[222:225], v[106:109]
	v_mfma_f32_16x16x32_bf16 v[102:105], v[130:133], v[230:233], v[102:105]
	v_mfma_f32_16x16x32_bf16 v[98:101], v[150:153], v[230:233], v[98:101]
	v_mfma_f32_16x16x32_bf16 v[126:129], v[134:137], v[210:213], v[126:129]
	v_mfma_f32_16x16x32_bf16 v[122:125], v[156:159], v[210:213], v[122:125]
	v_mfma_f32_16x16x32_bf16 v[118:121], v[134:137], v[218:221], v[118:121]
	v_mfma_f32_16x16x32_bf16 v[114:117], v[156:159], v[218:221], v[114:117]
	v_mfma_f32_16x16x32_bf16 v[110:113], v[134:137], v[226:229], v[110:113]
	v_mfma_f32_16x16x32_bf16 v[106:109], v[156:159], v[226:229], v[106:109]
	v_mfma_f32_16x16x32_bf16 v[102:105], v[134:137], v[234:237], v[102:105]
	v_mfma_f32_16x16x32_bf16 v[98:101], v[156:159], v[234:237], v[98:101]
	s_setprio 0
	s_setprio 1
	v_mfma_f32_16x16x32_bf16 v[66:69], v[160:163], v[206:209], v[66:69]
	v_mfma_f32_16x16x32_bf16 v[58:61], v[182:185], v[206:209], v[58:61]
	v_mfma_f32_16x16x32_bf16 v[54:57], v[160:163], v[214:217], v[54:57]
	v_mfma_f32_16x16x32_bf16 v[50:53], v[182:185], v[214:217], v[50:53]
	v_mfma_f32_16x16x32_bf16 v[46:49], v[160:163], v[222:225], v[46:49]
	v_mfma_f32_16x16x32_bf16 v[42:45], v[182:185], v[222:225], v[42:45]
	v_mfma_f32_16x16x32_bf16 v[38:41], v[160:163], v[230:233], v[38:41]
	v_mfma_f32_16x16x32_bf16 v[34:37], v[182:185], v[230:233], v[34:37]
	v_mfma_f32_16x16x32_bf16 v[66:69], v[178:181], v[210:213], v[66:69]
	v_mfma_f32_16x16x32_bf16 v[58:61], v[186:189], v[210:213], v[58:61]
	v_mfma_f32_16x16x32_bf16 v[54:57], v[178:181], v[218:221], v[54:57]
	v_mfma_f32_16x16x32_bf16 v[50:53], v[186:189], v[218:221], v[50:53]
	v_mfma_f32_16x16x32_bf16 v[46:49], v[178:181], v[226:229], v[46:49]
	v_mfma_f32_16x16x32_bf16 v[42:45], v[186:189], v[226:229], v[42:45]
	v_mfma_f32_16x16x32_bf16 v[38:41], v[178:181], v[234:237], v[38:41]
	v_mfma_f32_16x16x32_bf16 v[34:37], v[186:189], v[234:237], v[34:37]
	s_setprio 0
	s_barrier
	s_add_i32 s46, s48, s77
	s_mov_b32 m0, s46
	ds_read_b128 v[206:209], v155 offset:16384
	ds_read_b128 v[210:213], v155 offset:17408
	ds_read_b128 v[214:217], v155 offset:18432
	ds_read_b128 v[218:221], v155 offset:19456
	ds_read_b128 v[222:225], v155 offset:20480
	ds_read_b128 v[226:229], v155 offset:21504
	ds_read_b128 v[230:233], v155 offset:22528
	ds_read_b128 v[234:237], v155 offset:23552
	global_load_lds_dwordx4 v166, s[60:61]
	s_add_i32 m0, s46, 0x2000
	s_add_u32 s46, s60, 0x80000
	s_addc_u32 s47, s61, 0
	s_add_i32 s48, s49, s77
	global_load_lds_dwordx4 v142, s[60:61]
	s_mov_b32 m0, s48
	s_nop 0
	global_load_lds_dwordx4 v166, s[46:47]
	s_waitcnt vmcnt(5)
	s_waitcnt lgkmcnt(0)
	s_barrier
	s_setprio 1
	s_waitcnt lgkmcnt(0)
	v_mfma_f32_16x16x32_bf16 v[94:97], v[130:133], v[206:209], v[94:97]
	v_mfma_f32_16x16x32_bf16 v[90:93], v[150:153], v[206:209], v[90:93]
	v_mfma_f32_16x16x32_bf16 v[86:89], v[130:133], v[214:217], v[86:89]
	v_mfma_f32_16x16x32_bf16 v[82:85], v[150:153], v[214:217], v[82:85]
	v_mfma_f32_16x16x32_bf16 v[78:81], v[130:133], v[222:225], v[78:81]
	v_mfma_f32_16x16x32_bf16 v[74:77], v[150:153], v[222:225], v[74:77]
	s_add_i32 m0, s48, 0x2000
	s_nop 0
	global_load_lds_dwordx4 v142, s[46:47]
	v_mfma_f32_16x16x32_bf16 v[70:73], v[130:133], v[230:233], v[70:73]
	v_mfma_f32_16x16x32_bf16 v[62:65], v[150:153], v[230:233], v[62:65]
	v_mfma_f32_16x16x32_bf16 v[94:97], v[134:137], v[210:213], v[94:97]
	v_mfma_f32_16x16x32_bf16 v[90:93], v[156:159], v[210:213], v[90:93]
	v_mfma_f32_16x16x32_bf16 v[86:89], v[134:137], v[218:221], v[86:89]
	v_mfma_f32_16x16x32_bf16 v[82:85], v[156:159], v[218:221], v[82:85]
	v_mfma_f32_16x16x32_bf16 v[78:81], v[134:137], v[226:229], v[78:81]
	v_mfma_f32_16x16x32_bf16 v[74:77], v[156:159], v[226:229], v[74:77]
	v_mfma_f32_16x16x32_bf16 v[70:73], v[134:137], v[234:237], v[70:73]
	v_mfma_f32_16x16x32_bf16 v[62:65], v[156:159], v[234:237], v[62:65]
	s_mov_b32 m0, s67
	s_nop 0
	global_load_lds_dwordx4 v138, s[70:71]
	s_setprio 0
	s_setprio 1
	v_mfma_f32_16x16x32_bf16 v[30:33], v[160:163], v[206:209], v[30:33]
	v_mfma_f32_16x16x32_bf16 v[26:29], v[182:185], v[206:209], v[26:29]
	v_mfma_f32_16x16x32_bf16 v[22:25], v[160:163], v[214:217], v[22:25]
	v_mfma_f32_16x16x32_bf16 v[18:21], v[182:185], v[214:217], v[18:21]
	v_mfma_f32_16x16x32_bf16 v[14:17], v[160:163], v[222:225], v[14:17]
	v_mfma_f32_16x16x32_bf16 v[10:13], v[182:185], v[222:225], v[10:13]
	v_mfma_f32_16x16x32_bf16 v[6:9], v[160:163], v[230:233], v[6:9]
	v_mfma_f32_16x16x32_bf16 v[2:5], v[182:185], v[230:233], v[2:5]
	v_mfma_f32_16x16x32_bf16 v[30:33], v[178:181], v[210:213], v[30:33]
	v_mfma_f32_16x16x32_bf16 v[26:29], v[186:189], v[210:213], v[26:29]
	s_mov_b32 m0, s78
	s_nop 0
	global_load_lds_dwordx4 v140, s[70:71]
	v_mfma_f32_16x16x32_bf16 v[22:25], v[178:181], v[218:221], v[22:25]
	v_mfma_f32_16x16x32_bf16 v[18:21], v[186:189], v[218:221], v[18:21]
	v_mfma_f32_16x16x32_bf16 v[14:17], v[178:181], v[226:229], v[14:17]
	v_mfma_f32_16x16x32_bf16 v[10:13], v[186:189], v[226:229], v[10:13]
	v_mfma_f32_16x16x32_bf16 v[6:9], v[178:181], v[234:237], v[6:9]
	v_mfma_f32_16x16x32_bf16 v[2:5], v[186:189], v[234:237], v[2:5]
	s_setprio 0
	s_barrier
	s_add_i32 s48, 0, 0x18000
	s_add_i32 s49, 0, 0x1c000
	v_add_u32_e32 v156, s48, v1
	v_add_u32_e32 v186, s49, v1
	ds_read_b128 v[130:133], v156
	ds_read_b128 v[134:137], v156 offset:1024
	ds_read_b128 v[150:153], v156 offset:2048
	ds_read_b128 v[156:159], v156 offset:3072
	ds_read_b128 v[160:163], v186
	ds_read_b128 v[178:181], v186 offset:1024
	ds_read_b128 v[182:185], v186 offset:2048
	ds_read_b128 v[186:189], v186 offset:3072
	s_add_u32 s46, s70, 0x80000
	s_addc_u32 s47, s71, 0
	s_mov_b32 m0, s79
	ds_read_b128 v[206:209], v155 offset:32768
	ds_read_b128 v[210:213], v155 offset:33792
	ds_read_b128 v[214:217], v155 offset:34816
	ds_read_b128 v[218:221], v155 offset:35840
	ds_read_b128 v[222:225], v155 offset:36864
	ds_read_b128 v[226:229], v155 offset:37888
	ds_read_b128 v[230:233], v155 offset:38912
	ds_read_b128 v[234:237], v155 offset:39936
	global_load_lds_dwordx4 v138, s[46:47]
	s_mov_b32 m0, s80
	s_nop 0
	global_load_lds_dwordx4 v140, s[46:47]
	s_waitcnt vmcnt(8)
	s_waitcnt lgkmcnt(0)
	s_barrier
	s_setprio 1
	s_waitcnt lgkmcnt(0)
	v_mfma_f32_16x16x32_bf16 v[126:129], v[130:133], v[206:209], v[126:129]
	v_mfma_f32_16x16x32_bf16 v[122:125], v[150:153], v[206:209], v[122:125]
	v_mfma_f32_16x16x32_bf16 v[118:121], v[130:133], v[214:217], v[118:121]
	v_mfma_f32_16x16x32_bf16 v[114:117], v[150:153], v[214:217], v[114:117]
	v_mfma_f32_16x16x32_bf16 v[110:113], v[130:133], v[222:225], v[110:113]
	v_mfma_f32_16x16x32_bf16 v[106:109], v[150:153], v[222:225], v[106:109]
	v_mfma_f32_16x16x32_bf16 v[102:105], v[130:133], v[230:233], v[102:105]
	v_mfma_f32_16x16x32_bf16 v[98:101], v[150:153], v[230:233], v[98:101]
	v_mfma_f32_16x16x32_bf16 v[126:129], v[134:137], v[210:213], v[126:129]
	v_mfma_f32_16x16x32_bf16 v[122:125], v[156:159], v[210:213], v[122:125]
	v_mfma_f32_16x16x32_bf16 v[118:121], v[134:137], v[218:221], v[118:121]
	v_mfma_f32_16x16x32_bf16 v[114:117], v[156:159], v[218:221], v[114:117]
	v_mfma_f32_16x16x32_bf16 v[110:113], v[134:137], v[226:229], v[110:113]
	v_mfma_f32_16x16x32_bf16 v[106:109], v[156:159], v[226:229], v[106:109]
	v_mfma_f32_16x16x32_bf16 v[102:105], v[134:137], v[234:237], v[102:105]
	v_mfma_f32_16x16x32_bf16 v[98:101], v[156:159], v[234:237], v[98:101]
	s_setprio 0
	s_setprio 1
	v_mfma_f32_16x16x32_bf16 v[66:69], v[160:163], v[206:209], v[66:69]
	v_mfma_f32_16x16x32_bf16 v[58:61], v[182:185], v[206:209], v[58:61]
	v_mfma_f32_16x16x32_bf16 v[54:57], v[160:163], v[214:217], v[54:57]
	v_mfma_f32_16x16x32_bf16 v[50:53], v[182:185], v[214:217], v[50:53]
	v_mfma_f32_16x16x32_bf16 v[46:49], v[160:163], v[222:225], v[46:49]
	v_mfma_f32_16x16x32_bf16 v[42:45], v[182:185], v[222:225], v[42:45]
	v_mfma_f32_16x16x32_bf16 v[38:41], v[160:163], v[230:233], v[38:41]
	v_mfma_f32_16x16x32_bf16 v[34:37], v[182:185], v[230:233], v[34:37]
	v_mfma_f32_16x16x32_bf16 v[66:69], v[178:181], v[210:213], v[66:69]
	v_mfma_f32_16x16x32_bf16 v[58:61], v[186:189], v[210:213], v[58:61]
	v_mfma_f32_16x16x32_bf16 v[54:57], v[178:181], v[218:221], v[54:57]
	v_mfma_f32_16x16x32_bf16 v[50:53], v[186:189], v[218:221], v[50:53]
	v_mfma_f32_16x16x32_bf16 v[46:49], v[178:181], v[226:229], v[46:49]
	v_mfma_f32_16x16x32_bf16 v[42:45], v[186:189], v[226:229], v[42:45]
	v_mfma_f32_16x16x32_bf16 v[38:41], v[178:181], v[234:237], v[38:41]
	v_mfma_f32_16x16x32_bf16 v[34:37], v[186:189], v[234:237], v[34:37]
	s_setprio 0
	s_barrier
	s_add_i32 s46, s48, s77
	s_mov_b32 m0, s46
	ds_read_b128 v[206:209], v155 offset:49152
	ds_read_b128 v[210:213], v155 offset:50176
	ds_read_b128 v[214:217], v155 offset:51200
	ds_read_b128 v[218:221], v155 offset:52224
	ds_read_b128 v[222:225], v155 offset:53248
	ds_read_b128 v[226:229], v155 offset:54272
	ds_read_b128 v[230:233], v155 offset:55296
	ds_read_b128 v[234:237], v155 offset:56320
	s_add_u32 s100, s60, 128
	s_addc_u32 s101, s61, 0
	global_load_lds_dwordx4 v166, s[100:101]
	s_add_i32 m0, s46, 0x2000
	s_add_u32 s46, s60, 0x80080
	s_addc_u32 s47, s61, 0
	s_add_i32 s48, s49, s77
	s_add_u32 s100, s60, 128
	s_addc_u32 s101, s61, 0
	global_load_lds_dwordx4 v142, s[100:101]
	s_mov_b32 m0, s48
	s_nop 0
	global_load_lds_dwordx4 v166, s[46:47]
	s_waitcnt vmcnt(5)
	s_waitcnt lgkmcnt(0)
	s_barrier
	s_setprio 1
	s_waitcnt lgkmcnt(0)
	v_mfma_f32_16x16x32_bf16 v[94:97], v[130:133], v[206:209], v[94:97]
	v_mfma_f32_16x16x32_bf16 v[90:93], v[150:153], v[206:209], v[90:93]
	v_mfma_f32_16x16x32_bf16 v[86:89], v[130:133], v[214:217], v[86:89]
	v_mfma_f32_16x16x32_bf16 v[82:85], v[150:153], v[214:217], v[82:85]
	v_mfma_f32_16x16x32_bf16 v[78:81], v[130:133], v[222:225], v[78:81]
	v_mfma_f32_16x16x32_bf16 v[74:77], v[150:153], v[222:225], v[74:77]
	s_add_i32 m0, s48, 0x2000
	s_nop 0
	global_load_lds_dwordx4 v142, s[46:47]
	v_mfma_f32_16x16x32_bf16 v[70:73], v[130:133], v[230:233], v[70:73]
	v_mfma_f32_16x16x32_bf16 v[62:65], v[150:153], v[230:233], v[62:65]
	v_mfma_f32_16x16x32_bf16 v[94:97], v[134:137], v[210:213], v[94:97]
	v_mfma_f32_16x16x32_bf16 v[90:93], v[156:159], v[210:213], v[90:93]
	v_mfma_f32_16x16x32_bf16 v[86:89], v[134:137], v[218:221], v[86:89]
	v_mfma_f32_16x16x32_bf16 v[82:85], v[156:159], v[218:221], v[82:85]
	v_mfma_f32_16x16x32_bf16 v[78:81], v[134:137], v[226:229], v[78:81]
	v_mfma_f32_16x16x32_bf16 v[74:77], v[156:159], v[226:229], v[74:77]
	v_mfma_f32_16x16x32_bf16 v[70:73], v[134:137], v[234:237], v[70:73]
	v_mfma_f32_16x16x32_bf16 v[62:65], v[156:159], v[234:237], v[62:65]
	s_mov_b32 m0, s26
	s_nop 0
	s_add_u32 s100, s70, 128
	s_addc_u32 s101, s71, 0
	global_load_lds_dwordx4 v138, s[100:101]
	s_setprio 0
	s_setprio 1
	v_mfma_f32_16x16x32_bf16 v[30:33], v[160:163], v[206:209], v[30:33]
	v_mfma_f32_16x16x32_bf16 v[26:29], v[182:185], v[206:209], v[26:29]
	v_mfma_f32_16x16x32_bf16 v[22:25], v[160:163], v[214:217], v[22:25]
	v_mfma_f32_16x16x32_bf16 v[18:21], v[182:185], v[214:217], v[18:21]
	v_mfma_f32_16x16x32_bf16 v[14:17], v[160:163], v[222:225], v[14:17]
	v_mfma_f32_16x16x32_bf16 v[10:13], v[182:185], v[222:225], v[10:13]
	v_mfma_f32_16x16x32_bf16 v[6:9], v[160:163], v[230:233], v[6:9]
	v_mfma_f32_16x16x32_bf16 v[2:5], v[182:185], v[230:233], v[2:5]
	v_mfma_f32_16x16x32_bf16 v[30:33], v[178:181], v[210:213], v[30:33]
	v_mfma_f32_16x16x32_bf16 v[26:29], v[186:189], v[210:213], v[26:29]
	s_mov_b32 m0, s81
	s_nop 0
	s_add_u32 s100, s70, 128
	s_addc_u32 s101, s71, 0
	global_load_lds_dwordx4 v140, s[100:101]
	v_mfma_f32_16x16x32_bf16 v[22:25], v[178:181], v[218:221], v[22:25]
	v_mfma_f32_16x16x32_bf16 v[18:21], v[186:189], v[218:221], v[18:21]
	v_mfma_f32_16x16x32_bf16 v[14:17], v[178:181], v[226:229], v[14:17]
	v_mfma_f32_16x16x32_bf16 v[10:13], v[186:189], v[226:229], v[10:13]
	v_mfma_f32_16x16x32_bf16 v[6:9], v[178:181], v[234:237], v[6:9]
	v_mfma_f32_16x16x32_bf16 v[2:5], v[186:189], v[234:237], v[2:5]
	s_setprio 0
	s_barrier
	s_add_i32 s87, s87, 2
	s_add_u32 s68, s68, 0x100
	s_addc_u32 s69, s69, 0
	s_add_u32 s85, s85, 0x100
	s_addc_u32 s86, s86, 0
	s_cmp_gt_u32 s87, 29
	s_cbranch_scc0 .LBB0_795
	s_and_b64 vcc, exec, s[12:13]
	s_cbranch_vccz .LBB0_798
	s_barrier

.LBB0_819:
	s_add_i32 s93, s60, 2
	s_add_u32 s46, s72, 0x80
	s_addc_u32 s47, s73, 0
	s_add_i32 s48, 0, 0x10000
	s_cmp_eq_u32 s87, s60
	s_cselect_b32 s61, s23, s47
	s_cselect_b32 s60, s64, s46
	s_cselect_b32 s47, s21, s92
	s_cselect_b32 s46, s90, s91
	s_add_i32 s49, 0, 0x14000
	v_add_u32_e32 v142, s48, v205
	v_add_u32_e32 v182, s49, v205
	ds_read_b128 v[130:133], v142
	ds_read_b128 v[134:137], v142 offset:1024
	ds_read_b128 v[138:141], v142 offset:2048
	ds_read_b128 v[142:145], v142 offset:3072
	ds_read_b128 v[146:149], v182
	ds_read_b128 v[150:153], v182 offset:1024
	ds_read_b128 v[178:181], v182 offset:2048
	ds_read_b128 v[182:185], v182 offset:3072
	v_lshl_add_u64 v[236:237], s[72:73], 0, v[162:163]
	s_add_i32 m0, s71, 0xc000
	ds_read_b128 v[186:189], v207
	ds_read_b128 v[208:211], v207 offset:1024
	ds_read_b128 v[212:215], v207 offset:2048
	ds_read_b128 v[216:219], v207 offset:3072
	ds_read_b128 v[220:223], v207 offset:4096
	ds_read_b128 v[224:227], v207 offset:5120
	ds_read_b128 v[228:231], v207 offset:6144
	ds_read_b128 v[232:235], v207 offset:7168
	global_load_lds_dwordx4 v[236:237], off
	v_lshl_add_u64 v[236:237], s[72:73], 0, v[164:165]
	s_add_i32 m0, s71, 0xe000
	s_nop 0
	global_load_lds_dwordx4 v[236:237], off
	s_waitcnt vmcnt(8)
	s_waitcnt lgkmcnt(0)
	s_barrier
	s_setprio 1
	s_waitcnt lgkmcnt(0)
	v_mfma_f32_16x16x32_bf16 v[126:129], v[130:133], v[186:189], v[126:129]
	v_mfma_f32_16x16x32_bf16 v[122:125], v[138:141], v[186:189], v[122:125]
	v_mfma_f32_16x16x32_bf16 v[118:121], v[130:133], v[212:215], v[118:121]
	v_mfma_f32_16x16x32_bf16 v[114:117], v[138:141], v[212:215], v[114:117]
	v_mfma_f32_16x16x32_bf16 v[110:113], v[130:133], v[220:223], v[110:113]
	v_mfma_f32_16x16x32_bf16 v[106:109], v[138:141], v[220:223], v[106:109]
	v_mfma_f32_16x16x32_bf16 v[102:105], v[130:133], v[228:231], v[102:105]
	v_mfma_f32_16x16x32_bf16 v[98:101], v[138:141], v[228:231], v[98:101]
	v_mfma_f32_16x16x32_bf16 v[126:129], v[134:137], v[208:211], v[126:129]
	v_mfma_f32_16x16x32_bf16 v[122:125], v[142:145], v[208:211], v[122:125]
	v_mfma_f32_16x16x32_bf16 v[118:121], v[134:137], v[216:219], v[118:121]
	v_mfma_f32_16x16x32_bf16 v[114:117], v[142:145], v[216:219], v[114:117]
	v_mfma_f32_16x16x32_bf16 v[110:113], v[134:137], v[224:227], v[110:113]
	v_mfma_f32_16x16x32_bf16 v[106:109], v[142:145], v[224:227], v[106:109]
	v_mfma_f32_16x16x32_bf16 v[102:105], v[134:137], v[232:235], v[102:105]
	v_mfma_f32_16x16x32_bf16 v[98:101], v[142:145], v[232:235], v[98:101]
	s_setprio 0
	s_setprio 1
	v_mfma_f32_16x16x32_bf16 v[94:97], v[146:149], v[186:189], v[94:97]
	v_mfma_f32_16x16x32_bf16 v[90:93], v[178:181], v[186:189], v[90:93]
	v_mfma_f32_16x16x32_bf16 v[86:89], v[146:149], v[212:215], v[86:89]
	v_mfma_f32_16x16x32_bf16 v[82:85], v[178:181], v[212:215], v[82:85]
	v_mfma_f32_16x16x32_bf16 v[78:81], v[146:149], v[220:223], v[78:81]
	v_mfma_f32_16x16x32_bf16 v[74:77], v[178:181], v[220:223], v[74:77]
	v_mfma_f32_16x16x32_bf16 v[70:73], v[146:149], v[228:231], v[70:73]
	v_mfma_f32_16x16x32_bf16 v[66:69], v[178:181], v[228:231], v[66:69]
	v_mfma_f32_16x16x32_bf16 v[94:97], v[150:153], v[208:211], v[94:97]
	v_mfma_f32_16x16x32_bf16 v[90:93], v[182:185], v[208:211], v[90:93]
	v_mfma_f32_16x16x32_bf16 v[86:89], v[150:153], v[216:219], v[86:89]
	v_mfma_f32_16x16x32_bf16 v[82:85], v[182:185], v[216:219], v[82:85]
	v_mfma_f32_16x16x32_bf16 v[78:81], v[150:153], v[224:227], v[78:81]
	v_mfma_f32_16x16x32_bf16 v[74:77], v[182:185], v[224:227], v[74:77]
	v_mfma_f32_16x16x32_bf16 v[70:73], v[150:153], v[232:235], v[70:73]
	v_mfma_f32_16x16x32_bf16 v[66:69], v[182:185], v[232:235], v[66:69]
	s_setprio 0
	s_barrier
	s_add_i32 s48, s48, s80
	v_lshl_add_u64 v[236:237], s[46:47], 0, v[166:167]
	s_mov_b32 m0, s48
	ds_read_b128 v[186:189], v207 offset:16384
	ds_read_b128 v[208:211], v207 offset:17408
	ds_read_b128 v[212:215], v207 offset:18432
	ds_read_b128 v[216:219], v207 offset:19456
	ds_read_b128 v[220:223], v207 offset:20480
	ds_read_b128 v[224:227], v207 offset:21504
	ds_read_b128 v[228:231], v207 offset:22528
	ds_read_b128 v[232:235], v207 offset:23552
	global_load_lds_dwordx4 v166, s[46:47]
	s_add_i32 m0, s48, 0x2000
	v_lshl_add_u64 v[242:243], s[46:47], 0, v[158:159]
	s_add_u32 s46, s46, s26
	s_addc_u32 s47, s47, 0
	s_add_i32 s48, s49, s80
	global_load_lds_dwordx4 v[242:243], off
	v_lshl_add_u64 v[244:245], s[46:47], 0, v[166:167]
	s_mov_b32 m0, s48
	v_lshl_add_u64 v[246:247], s[46:47], 0, v[158:159]
	global_load_lds_dwordx4 v166, s[46:47]
	s_add_i32 m0, s48, 0x2000
	s_nop 0
	global_load_lds_dwordx4 v158, s[46:47]
	s_mov_b32 m0, s71
	s_nop 0
	global_load_lds_dwordx4 v154, s[60:61]
	s_mov_b32 m0, s81
	s_nop 0
	global_load_lds_dwordx4 v156, s[60:61]
	s_waitcnt vmcnt(8)
	s_waitcnt lgkmcnt(0)
	s_barrier
	s_setprio 1
	s_waitcnt lgkmcnt(0)
	v_mfma_f32_16x16x32_bf16 v[62:65], v[130:133], v[186:189], v[62:65]
	v_mfma_f32_16x16x32_bf16 v[58:61], v[138:141], v[186:189], v[58:61]
	v_mfma_f32_16x16x32_bf16 v[54:57], v[130:133], v[212:215], v[54:57]
	v_mfma_f32_16x16x32_bf16 v[50:53], v[138:141], v[212:215], v[50:53]
	v_mfma_f32_16x16x32_bf16 v[46:49], v[130:133], v[220:223], v[46:49]
	v_mfma_f32_16x16x32_bf16 v[42:45], v[138:141], v[220:223], v[42:45]
	v_mfma_f32_16x16x32_bf16 v[38:41], v[130:133], v[228:231], v[38:41]
	v_mfma_f32_16x16x32_bf16 v[34:37], v[138:141], v[228:231], v[34:37]
	v_mfma_f32_16x16x32_bf16 v[62:65], v[134:137], v[208:211], v[62:65]
	v_mfma_f32_16x16x32_bf16 v[58:61], v[142:145], v[208:211], v[58:61]
	v_mfma_f32_16x16x32_bf16 v[54:57], v[134:137], v[216:219], v[54:57]
	v_mfma_f32_16x16x32_bf16 v[50:53], v[142:145], v[216:219], v[50:53]
	v_mfma_f32_16x16x32_bf16 v[46:49], v[134:137], v[224:227], v[46:49]
	v_mfma_f32_16x16x32_bf16 v[42:45], v[142:145], v[224:227], v[42:45]
	v_mfma_f32_16x16x32_bf16 v[38:41], v[134:137], v[232:235], v[38:41]
	v_mfma_f32_16x16x32_bf16 v[34:37], v[142:145], v[232:235], v[34:37]
	s_setprio 0
	s_setprio 1
	v_mfma_f32_16x16x32_bf16 v[30:33], v[146:149], v[186:189], v[30:33]
	v_mfma_f32_16x16x32_bf16 v[26:29], v[178:181], v[186:189], v[26:29]
	v_mfma_f32_16x16x32_bf16 v[22:25], v[146:149], v[212:215], v[22:25]
	v_mfma_f32_16x16x32_bf16 v[18:21], v[178:181], v[212:215], v[18:21]
	v_mfma_f32_16x16x32_bf16 v[14:17], v[146:149], v[220:223], v[14:17]
	v_mfma_f32_16x16x32_bf16 v[10:13], v[178:181], v[220:223], v[10:13]
	v_mfma_f32_16x16x32_bf16 v[6:9], v[146:149], v[228:231], v[6:9]
	v_mfma_f32_16x16x32_bf16 v[2:5], v[178:181], v[228:231], v[2:5]
	v_mfma_f32_16x16x32_bf16 v[30:33], v[150:153], v[208:211], v[30:33]
	v_mfma_f32_16x16x32_bf16 v[26:29], v[182:185], v[208:211], v[26:29]
	v_mfma_f32_16x16x32_bf16 v[22:25], v[150:153], v[216:219], v[22:25]
	v_mfma_f32_16x16x32_bf16 v[18:21], v[182:185], v[216:219], v[18:21]
	v_mfma_f32_16x16x32_bf16 v[14:17], v[150:153], v[224:227], v[14:17]
	v_mfma_f32_16x16x32_bf16 v[10:13], v[182:185], v[224:227], v[10:13]
	v_mfma_f32_16x16x32_bf16 v[6:9], v[150:153], v[232:235], v[6:9]
	v_mfma_f32_16x16x32_bf16 v[2:5], v[182:185], v[232:235], v[2:5]
	s_setprio 0
	s_barrier
	s_add_i32 s48, 0, 0x18000
	s_add_i32 s49, 0, 0x1c000
	v_add_u32_e32 v142, s48, v205
	v_add_u32_e32 v182, s49, v205
	ds_read_b128 v[130:133], v142
	ds_read_b128 v[134:137], v142 offset:1024
	ds_read_b128 v[138:141], v142 offset:2048
	ds_read_b128 v[142:145], v142 offset:3072
	ds_read_b128 v[146:149], v182
	ds_read_b128 v[150:153], v182 offset:1024
	ds_read_b128 v[178:181], v182 offset:2048
	ds_read_b128 v[182:185], v182 offset:3072
	s_add_u32 s46, s60, s26
	s_addc_u32 s47, s61, 0
	s_mov_b32 m0, s82
	ds_read_b128 v[186:189], v207 offset:32768
	ds_read_b128 v[208:211], v207 offset:33792
	ds_read_b128 v[212:215], v207 offset:34816
	ds_read_b128 v[216:219], v207 offset:35840
	ds_read_b128 v[220:223], v207 offset:36864
	ds_read_b128 v[224:227], v207 offset:37888
	ds_read_b128 v[228:231], v207 offset:38912
	ds_read_b128 v[232:235], v207 offset:39936
	global_load_lds_dwordx4 v154, s[46:47]
	s_mov_b32 m0, s83
	s_nop 0
	global_load_lds_dwordx4 v156, s[46:47]
	s_waitcnt vmcnt(8)
	s_waitcnt lgkmcnt(0)
	s_barrier
	s_setprio 1
	s_waitcnt lgkmcnt(0)
	v_mfma_f32_16x16x32_bf16 v[126:129], v[130:133], v[186:189], v[126:129]
	v_mfma_f32_16x16x32_bf16 v[122:125], v[138:141], v[186:189], v[122:125]
	v_mfma_f32_16x16x32_bf16 v[118:121], v[130:133], v[212:215], v[118:121]
	v_mfma_f32_16x16x32_bf16 v[114:117], v[138:141], v[212:215], v[114:117]
	v_mfma_f32_16x16x32_bf16 v[110:113], v[130:133], v[220:223], v[110:113]
	v_mfma_f32_16x16x32_bf16 v[106:109], v[138:141], v[220:223], v[106:109]
	v_mfma_f32_16x16x32_bf16 v[102:105], v[130:133], v[228:231], v[102:105]
	v_mfma_f32_16x16x32_bf16 v[98:101], v[138:141], v[228:231], v[98:101]
	v_mfma_f32_16x16x32_bf16 v[126:129], v[134:137], v[208:211], v[126:129]
	v_mfma_f32_16x16x32_bf16 v[122:125], v[142:145], v[208:211], v[122:125]
	v_mfma_f32_16x16x32_bf16 v[118:121], v[134:137], v[216:219], v[118:121]
	v_mfma_f32_16x16x32_bf16 v[114:117], v[142:145], v[216:219], v[114:117]
	v_mfma_f32_16x16x32_bf16 v[110:113], v[134:137], v[224:227], v[110:113]
	v_mfma_f32_16x16x32_bf16 v[106:109], v[142:145], v[224:227], v[106:109]
	v_mfma_f32_16x16x32_bf16 v[102:105], v[134:137], v[232:235], v[102:105]
	v_mfma_f32_16x16x32_bf16 v[98:101], v[142:145], v[232:235], v[98:101]
	s_setprio 0
	s_setprio 1
	v_mfma_f32_16x16x32_bf16 v[94:97], v[146:149], v[186:189], v[94:97]
	v_mfma_f32_16x16x32_bf16 v[90:93], v[178:181], v[186:189], v[90:93]
	v_mfma_f32_16x16x32_bf16 v[86:89], v[146:149], v[212:215], v[86:89]
	v_mfma_f32_16x16x32_bf16 v[82:85], v[178:181], v[212:215], v[82:85]
	v_mfma_f32_16x16x32_bf16 v[78:81], v[146:149], v[220:223], v[78:81]
	v_mfma_f32_16x16x32_bf16 v[74:77], v[178:181], v[220:223], v[74:77]
	v_mfma_f32_16x16x32_bf16 v[70:73], v[146:149], v[228:231], v[70:73]
	v_mfma_f32_16x16x32_bf16 v[66:69], v[178:181], v[228:231], v[66:69]
	v_mfma_f32_16x16x32_bf16 v[94:97], v[150:153], v[208:211], v[94:97]
	v_mfma_f32_16x16x32_bf16 v[90:93], v[182:185], v[208:211], v[90:93]
	v_mfma_f32_16x16x32_bf16 v[86:89], v[150:153], v[216:219], v[86:89]
	v_mfma_f32_16x16x32_bf16 v[82:85], v[182:185], v[216:219], v[82:85]
	v_mfma_f32_16x16x32_bf16 v[78:81], v[150:153], v[224:227], v[78:81]
	v_mfma_f32_16x16x32_bf16 v[74:77], v[182:185], v[224:227], v[74:77]
	v_mfma_f32_16x16x32_bf16 v[70:73], v[150:153], v[232:235], v[70:73]
	v_mfma_f32_16x16x32_bf16 v[66:69], v[182:185], v[232:235], v[66:69]
	s_setprio 0
	s_barrier
	s_add_i32 s46, s48, s80
	v_lshl_add_u64 v[236:237], v[236:237], 0, s[42:43]
	s_mov_b32 m0, s46
	ds_read_b128 v[186:189], v207 offset:49152
	ds_read_b128 v[208:211], v207 offset:50176
	ds_read_b128 v[212:215], v207 offset:51200
	ds_read_b128 v[216:219], v207 offset:52224
	ds_read_b128 v[220:223], v207 offset:53248
	ds_read_b128 v[224:227], v207 offset:54272
	ds_read_b128 v[228:231], v207 offset:55296
	ds_read_b128 v[232:235], v207 offset:56320
	global_load_lds_dwordx4 v[236:237], off
	v_lshl_add_u64 v[236:237], v[242:243], 0, s[42:43]
	s_add_i32 m0, s46, 0x2000
	s_add_i32 s46, s49, s80
	global_load_lds_dwordx4 v[236:237], off
	v_lshl_add_u64 v[236:237], v[244:245], 0, s[42:43]
	s_mov_b32 m0, s46
	s_nop 0
	global_load_lds_dwordx4 v[236:237], off
	v_lshl_add_u64 v[236:237], v[246:247], 0, s[42:43]
	s_add_i32 m0, s46, 0x2000
	s_nop 0
	global_load_lds_dwordx4 v[236:237], off
	s_mov_b32 m0, s85
	s_nop 0
	s_add_u32 s100, s60, 128
	s_addc_u32 s101, s61, 0
	global_load_lds_dwordx4 v154, s[100:101]
	s_mov_b32 m0, s86
	s_nop 0
	s_add_u32 s100, s60, 128
	s_addc_u32 s101, s61, 0
	global_load_lds_dwordx4 v156, s[100:101]
	s_waitcnt vmcnt(8)
	s_waitcnt lgkmcnt(0)
	s_barrier
	s_setprio 1
	s_waitcnt lgkmcnt(0)
	v_mfma_f32_16x16x32_bf16 v[62:65], v[130:133], v[186:189], v[62:65]
	v_mfma_f32_16x16x32_bf16 v[58:61], v[138:141], v[186:189], v[58:61]
	v_mfma_f32_16x16x32_bf16 v[54:57], v[130:133], v[212:215], v[54:57]
	v_mfma_f32_16x16x32_bf16 v[50:53], v[138:141], v[212:215], v[50:53]
	v_mfma_f32_16x16x32_bf16 v[46:49], v[130:133], v[220:223], v[46:49]
	v_mfma_f32_16x16x32_bf16 v[42:45], v[138:141], v[220:223], v[42:45]
	v_mfma_f32_16x16x32_bf16 v[38:41], v[130:133], v[228:231], v[38:41]
	v_mfma_f32_16x16x32_bf16 v[34:37], v[138:141], v[228:231], v[34:37]
	v_mfma_f32_16x16x32_bf16 v[62:65], v[134:137], v[208:211], v[62:65]
	v_mfma_f32_16x16x32_bf16 v[58:61], v[142:145], v[208:211], v[58:61]
	v_mfma_f32_16x16x32_bf16 v[54:57], v[134:137], v[216:219], v[54:57]
	v_mfma_f32_16x16x32_bf16 v[50:53], v[142:145], v[216:219], v[50:53]
	v_mfma_f32_16x16x32_bf16 v[46:49], v[134:137], v[224:227], v[46:49]
	v_mfma_f32_16x16x32_bf16 v[42:45], v[142:145], v[224:227], v[42:45]
	v_mfma_f32_16x16x32_bf16 v[38:41], v[134:137], v[232:235], v[38:41]
	v_mfma_f32_16x16x32_bf16 v[34:37], v[142:145], v[232:235], v[34:37]
	s_setprio 0
	s_setprio 1
	v_mfma_f32_16x16x32_bf16 v[30:33], v[146:149], v[186:189], v[30:33]
	v_mfma_f32_16x16x32_bf16 v[26:29], v[178:181], v[186:189], v[26:29]
	v_mfma_f32_16x16x32_bf16 v[22:25], v[146:149], v[212:215], v[22:25]
	v_mfma_f32_16x16x32_bf16 v[18:21], v[178:181], v[212:215], v[18:21]
	v_mfma_f32_16x16x32_bf16 v[14:17], v[146:149], v[220:223], v[14:17]
	v_mfma_f32_16x16x32_bf16 v[10:13], v[178:181], v[220:223], v[10:13]
	v_mfma_f32_16x16x32_bf16 v[6:9], v[146:149], v[228:231], v[6:9]
	v_mfma_f32_16x16x32_bf16 v[2:5], v[178:181], v[228:231], v[2:5]
	v_mfma_f32_16x16x32_bf16 v[30:33], v[150:153], v[208:211], v[30:33]
	v_mfma_f32_16x16x32_bf16 v[26:29], v[182:185], v[208:211], v[26:29]
	v_mfma_f32_16x16x32_bf16 v[22:25], v[150:153], v[216:219], v[22:25]
	v_mfma_f32_16x16x32_bf16 v[18:21], v[182:185], v[216:219], v[18:21]
	v_mfma_f32_16x16x32_bf16 v[14:17], v[150:153], v[224:227], v[14:17]
	v_mfma_f32_16x16x32_bf16 v[10:13], v[182:185], v[224:227], v[10:13]
	v_mfma_f32_16x16x32_bf16 v[6:9], v[150:153], v[232:235], v[6:9]
	v_mfma_f32_16x16x32_bf16 v[2:5], v[182:185], v[232:235], v[2:5]
	s_setprio 0
	s_barrier
	s_add_u32 s72, s72, 0x100
	s_addc_u32 s73, s73, 0
	s_add_u32 s91, s91, 0x100
	s_addc_u32 s92, s92, 0
	s_cmp_ge_u32 s93, s84
	s_mov_b32 s60, s93
	s_cbranch_scc0 .LBB0_819
	s_and_b64 vcc, exec, s[18:19]
	s_cbranch_vccz .LBB0_822
	s_barrier

.LBB0_903:
	s_add_u32 s46, s66, 0xfff80080
	s_addc_u32 s47, s67, -1
	s_add_i32 s48, 0, 0x10000
	s_cmp_eq_u32 s84, 28
	s_cselect_b32 s69, s17, s47
	s_cselect_b32 s68, s64, s46
	s_cselect_b32 s61, s13, s83
	s_cselect_b32 s60, s81, s82
	s_add_i32 s49, 0, 0x14000
	v_add_u32_e32 v142, s48, v186
	v_add_u32_e32 v164, s49, v186
	ds_read_b128 v[130:133], v142
	ds_read_b128 v[134:137], v142 offset:1024
	ds_read_b128 v[138:141], v142 offset:2048
	ds_read_b128 v[142:145], v142 offset:3072
	ds_read_b128 v[146:149], v164
	ds_read_b128 v[160:163], v164 offset:1024
	ds_read_b128 v[178:181], v164 offset:2048
	ds_read_b128 v[182:185], v164 offset:3072
	s_add_i32 m0, s74, 0xc000
	ds_read_b128 v[206:209], v188
	ds_read_b128 v[210:213], v188 offset:1024
	ds_read_b128 v[214:217], v188 offset:2048
	ds_read_b128 v[218:221], v188 offset:3072
	ds_read_b128 v[222:225], v188 offset:4096
	ds_read_b128 v[226:229], v188 offset:5120
	ds_read_b128 v[230:233], v188 offset:6144
	ds_read_b128 v[234:237], v188 offset:7168
	global_load_lds_dwordx4 v156, s[66:67]
	s_add_i32 m0, s74, 0xe000
	s_nop 0
	global_load_lds_dwordx4 v158, s[66:67]
	s_waitcnt vmcnt(8)
	s_waitcnt lgkmcnt(0)
	s_barrier
	s_setprio 1
	s_waitcnt lgkmcnt(0)
	v_mfma_f32_16x16x32_bf16 v[126:129], v[130:133], v[206:209], v[126:129]
	v_mfma_f32_16x16x32_bf16 v[122:125], v[138:141], v[206:209], v[122:125]
	v_mfma_f32_16x16x32_bf16 v[118:121], v[130:133], v[214:217], v[118:121]
	v_mfma_f32_16x16x32_bf16 v[110:113], v[138:141], v[214:217], v[110:113]
	v_mfma_f32_16x16x32_bf16 v[94:97], v[130:133], v[222:225], v[94:97]
	v_mfma_f32_16x16x32_bf16 v[90:93], v[138:141], v[222:225], v[90:93]
	v_mfma_f32_16x16x32_bf16 v[82:85], v[130:133], v[230:233], v[82:85]
	v_mfma_f32_16x16x32_bf16 v[74:77], v[138:141], v[230:233], v[74:77]
	v_mfma_f32_16x16x32_bf16 v[126:129], v[134:137], v[210:213], v[126:129]
	v_mfma_f32_16x16x32_bf16 v[122:125], v[142:145], v[210:213], v[122:125]
	v_mfma_f32_16x16x32_bf16 v[118:121], v[134:137], v[218:221], v[118:121]
	v_mfma_f32_16x16x32_bf16 v[110:113], v[142:145], v[218:221], v[110:113]
	v_mfma_f32_16x16x32_bf16 v[94:97], v[134:137], v[226:229], v[94:97]
	v_mfma_f32_16x16x32_bf16 v[90:93], v[142:145], v[226:229], v[90:93]
	v_mfma_f32_16x16x32_bf16 v[82:85], v[134:137], v[234:237], v[82:85]
	v_mfma_f32_16x16x32_bf16 v[74:77], v[142:145], v[234:237], v[74:77]
	s_setprio 0
	s_setprio 1
	v_mfma_f32_16x16x32_bf16 v[114:117], v[146:149], v[206:209], v[114:117]
	v_mfma_f32_16x16x32_bf16 v[106:109], v[178:181], v[206:209], v[106:109]
	v_mfma_f32_16x16x32_bf16 v[102:105], v[146:149], v[214:217], v[102:105]
	v_mfma_f32_16x16x32_bf16 v[98:101], v[178:181], v[214:217], v[98:101]
	v_mfma_f32_16x16x32_bf16 v[86:89], v[146:149], v[222:225], v[86:89]
	v_mfma_f32_16x16x32_bf16 v[78:81], v[178:181], v[222:225], v[78:81]
	v_mfma_f32_16x16x32_bf16 v[70:73], v[146:149], v[230:233], v[70:73]
	v_mfma_f32_16x16x32_bf16 v[66:69], v[178:181], v[230:233], v[66:69]
	v_mfma_f32_16x16x32_bf16 v[114:117], v[160:163], v[210:213], v[114:117]
	v_mfma_f32_16x16x32_bf16 v[106:109], v[182:185], v[210:213], v[106:109]
	v_mfma_f32_16x16x32_bf16 v[102:105], v[160:163], v[218:221], v[102:105]
	v_mfma_f32_16x16x32_bf16 v[98:101], v[182:185], v[218:221], v[98:101]
	v_mfma_f32_16x16x32_bf16 v[86:89], v[160:163], v[226:229], v[86:89]
	v_mfma_f32_16x16x32_bf16 v[78:81], v[182:185], v[226:229], v[78:81]
	v_mfma_f32_16x16x32_bf16 v[70:73], v[160:163], v[234:237], v[70:73]
	v_mfma_f32_16x16x32_bf16 v[66:69], v[182:185], v[234:237], v[66:69]
	s_setprio 0
	s_barrier
	s_add_i32 s46, s48, s73
	s_mov_b32 m0, s46
	ds_read_b128 v[206:209], v188 offset:16384
	ds_read_b128 v[210:213], v188 offset:17408
	ds_read_b128 v[214:217], v188 offset:18432
	ds_read_b128 v[218:221], v188 offset:19456
	ds_read_b128 v[222:225], v188 offset:20480
	ds_read_b128 v[226:229], v188 offset:21504
	ds_read_b128 v[230:233], v188 offset:22528
	ds_read_b128 v[234:237], v188 offset:23552
	global_load_lds_dwordx4 v166, s[60:61]
	s_add_i32 m0, s46, 0x2000
	s_add_u32 s46, s60, 0x80000
	s_addc_u32 s47, s61, 0
	s_add_i32 s48, s49, s73
	global_load_lds_dwordx4 v154, s[60:61]
	s_mov_b32 m0, s48
	s_nop 0
	global_load_lds_dwordx4 v166, s[46:47]
	s_waitcnt vmcnt(5)
	s_waitcnt lgkmcnt(0)
	s_barrier
	s_setprio 1
	s_waitcnt lgkmcnt(0)
	v_mfma_f32_16x16x32_bf16 v[62:65], v[130:133], v[206:209], v[62:65]
	v_mfma_f32_16x16x32_bf16 v[58:61], v[138:141], v[206:209], v[58:61]
	v_mfma_f32_16x16x32_bf16 v[50:53], v[130:133], v[214:217], v[50:53]
	v_mfma_f32_16x16x32_bf16 v[42:45], v[138:141], v[214:217], v[42:45]
	v_mfma_f32_16x16x32_bf16 v[34:37], v[130:133], v[222:225], v[34:37]
	v_mfma_f32_16x16x32_bf16 v[26:29], v[138:141], v[222:225], v[26:29]
	s_add_i32 m0, s48, 0x2000
	s_nop 0
	global_load_lds_dwordx4 v154, s[46:47]
	v_mfma_f32_16x16x32_bf16 v[18:21], v[130:133], v[230:233], v[18:21]
	v_mfma_f32_16x16x32_bf16 v[10:13], v[138:141], v[230:233], v[10:13]
	v_mfma_f32_16x16x32_bf16 v[62:65], v[134:137], v[210:213], v[62:65]
	v_mfma_f32_16x16x32_bf16 v[58:61], v[142:145], v[210:213], v[58:61]
	v_mfma_f32_16x16x32_bf16 v[50:53], v[134:137], v[218:221], v[50:53]
	v_mfma_f32_16x16x32_bf16 v[42:45], v[142:145], v[218:221], v[42:45]
	v_mfma_f32_16x16x32_bf16 v[34:37], v[134:137], v[226:229], v[34:37]
	v_mfma_f32_16x16x32_bf16 v[26:29], v[142:145], v[226:229], v[26:29]
	v_mfma_f32_16x16x32_bf16 v[18:21], v[134:137], v[234:237], v[18:21]
	v_mfma_f32_16x16x32_bf16 v[10:13], v[142:145], v[234:237], v[10:13]
	s_mov_b32 m0, s74
	s_nop 0
	global_load_lds_dwordx4 v150, s[68:69]
	s_setprio 0
	s_setprio 1
	v_mfma_f32_16x16x32_bf16 v[54:57], v[146:149], v[206:209], v[54:57]
	v_mfma_f32_16x16x32_bf16 v[46:49], v[178:181], v[206:209], v[46:49]
	v_mfma_f32_16x16x32_bf16 v[38:41], v[146:149], v[214:217], v[38:41]
	v_mfma_f32_16x16x32_bf16 v[30:33], v[178:181], v[214:217], v[30:33]
	v_mfma_f32_16x16x32_bf16 v[22:25], v[146:149], v[222:225], v[22:25]
	v_mfma_f32_16x16x32_bf16 v[14:17], v[178:181], v[222:225], v[14:17]
	v_mfma_f32_16x16x32_bf16 v[6:9], v[146:149], v[230:233], v[6:9]
	v_mfma_f32_16x16x32_bf16 v[2:5], v[178:181], v[230:233], v[2:5]
	v_mfma_f32_16x16x32_bf16 v[54:57], v[160:163], v[210:213], v[54:57]
	v_mfma_f32_16x16x32_bf16 v[46:49], v[182:185], v[210:213], v[46:49]
	s_mov_b32 m0, s75
	s_nop 0
	global_load_lds_dwordx4 v152, s[68:69]
	v_mfma_f32_16x16x32_bf16 v[38:41], v[160:163], v[218:221], v[38:41]
	v_mfma_f32_16x16x32_bf16 v[30:33], v[182:185], v[218:221], v[30:33]
	v_mfma_f32_16x16x32_bf16 v[22:25], v[160:163], v[226:229], v[22:25]
	v_mfma_f32_16x16x32_bf16 v[14:17], v[182:185], v[226:229], v[14:17]
	v_mfma_f32_16x16x32_bf16 v[6:9], v[160:163], v[234:237], v[6:9]
	v_mfma_f32_16x16x32_bf16 v[2:5], v[182:185], v[234:237], v[2:5]
	s_setprio 0
	s_barrier
	s_add_i32 s48, 0, 0x18000
	s_add_i32 s49, 0, 0x1c000
	v_add_u32_e32 v142, s48, v186
	v_add_u32_e32 v182, s49, v186
	ds_read_b128 v[130:133], v142
	ds_read_b128 v[134:137], v142 offset:1024
	ds_read_b128 v[138:141], v142 offset:2048
	ds_read_b128 v[142:145], v142 offset:3072
	ds_read_b128 v[146:149], v182
	ds_read_b128 v[160:163], v182 offset:1024
	ds_read_b128 v[178:181], v182 offset:2048
	ds_read_b128 v[182:185], v182 offset:3072
	s_add_u32 s46, s68, 0x80000
	s_addc_u32 s47, s69, 0
	s_mov_b32 m0, s76
	ds_read_b128 v[206:209], v188 offset:32768
	ds_read_b128 v[210:213], v188 offset:33792
	ds_read_b128 v[214:217], v188 offset:34816
	ds_read_b128 v[218:221], v188 offset:35840
	ds_read_b128 v[222:225], v188 offset:36864
	ds_read_b128 v[226:229], v188 offset:37888
	ds_read_b128 v[230:233], v188 offset:38912
	ds_read_b128 v[234:237], v188 offset:39936
	global_load_lds_dwordx4 v150, s[46:47]
	s_mov_b32 m0, s77
	s_nop 0
	global_load_lds_dwordx4 v152, s[46:47]
	s_waitcnt vmcnt(8)
	s_waitcnt lgkmcnt(0)
	s_barrier
	s_setprio 1
	s_waitcnt lgkmcnt(0)
	v_mfma_f32_16x16x32_bf16 v[126:129], v[130:133], v[206:209], v[126:129]
	v_mfma_f32_16x16x32_bf16 v[122:125], v[138:141], v[206:209], v[122:125]
	v_mfma_f32_16x16x32_bf16 v[118:121], v[130:133], v[214:217], v[118:121]
	v_mfma_f32_16x16x32_bf16 v[110:113], v[138:141], v[214:217], v[110:113]
	v_mfma_f32_16x16x32_bf16 v[94:97], v[130:133], v[222:225], v[94:97]
	v_mfma_f32_16x16x32_bf16 v[90:93], v[138:141], v[222:225], v[90:93]
	v_mfma_f32_16x16x32_bf16 v[82:85], v[130:133], v[230:233], v[82:85]
	v_mfma_f32_16x16x32_bf16 v[74:77], v[138:141], v[230:233], v[74:77]
	v_mfma_f32_16x16x32_bf16 v[126:129], v[134:137], v[210:213], v[126:129]
	v_mfma_f32_16x16x32_bf16 v[122:125], v[142:145], v[210:213], v[122:125]
	v_mfma_f32_16x16x32_bf16 v[118:121], v[134:137], v[218:221], v[118:121]
	v_mfma_f32_16x16x32_bf16 v[110:113], v[142:145], v[218:221], v[110:113]
	v_mfma_f32_16x16x32_bf16 v[94:97], v[134:137], v[226:229], v[94:97]
	v_mfma_f32_16x16x32_bf16 v[90:93], v[142:145], v[226:229], v[90:93]
	v_mfma_f32_16x16x32_bf16 v[82:85], v[134:137], v[234:237], v[82:85]
	v_mfma_f32_16x16x32_bf16 v[74:77], v[142:145], v[234:237], v[74:77]
	s_setprio 0
	s_setprio 1
	v_mfma_f32_16x16x32_bf16 v[114:117], v[146:149], v[206:209], v[114:117]
	v_mfma_f32_16x16x32_bf16 v[106:109], v[178:181], v[206:209], v[106:109]
	v_mfma_f32_16x16x32_bf16 v[102:105], v[146:149], v[214:217], v[102:105]
	v_mfma_f32_16x16x32_bf16 v[98:101], v[178:181], v[214:217], v[98:101]
	v_mfma_f32_16x16x32_bf16 v[86:89], v[146:149], v[222:225], v[86:89]
	v_mfma_f32_16x16x32_bf16 v[78:81], v[178:181], v[222:225], v[78:81]
	v_mfma_f32_16x16x32_bf16 v[70:73], v[146:149], v[230:233], v[70:73]
	v_mfma_f32_16x16x32_bf16 v[66:69], v[178:181], v[230:233], v[66:69]
	v_mfma_f32_16x16x32_bf16 v[114:117], v[160:163], v[210:213], v[114:117]
	v_mfma_f32_16x16x32_bf16 v[106:109], v[182:185], v[210:213], v[106:109]
	v_mfma_f32_16x16x32_bf16 v[102:105], v[160:163], v[218:221], v[102:105]
	v_mfma_f32_16x16x32_bf16 v[98:101], v[182:185], v[218:221], v[98:101]
	v_mfma_f32_16x16x32_bf16 v[86:89], v[160:163], v[226:229], v[86:89]
	v_mfma_f32_16x16x32_bf16 v[78:81], v[182:185], v[226:229], v[78:81]
	v_mfma_f32_16x16x32_bf16 v[70:73], v[160:163], v[234:237], v[70:73]
	v_mfma_f32_16x16x32_bf16 v[66:69], v[182:185], v[234:237], v[66:69]
	s_setprio 0
	s_barrier
	s_add_i32 s46, s48, s73
	s_mov_b32 m0, s46
	ds_read_b128 v[206:209], v188 offset:49152
	ds_read_b128 v[210:213], v188 offset:50176
	ds_read_b128 v[214:217], v188 offset:51200
	ds_read_b128 v[218:221], v188 offset:52224
	ds_read_b128 v[222:225], v188 offset:53248
	ds_read_b128 v[226:229], v188 offset:54272
	ds_read_b128 v[230:233], v188 offset:55296
	ds_read_b128 v[234:237], v188 offset:56320
	s_add_u32 s100, s60, 128
	s_addc_u32 s101, s61, 0
	global_load_lds_dwordx4 v166, s[100:101]
	s_add_i32 m0, s46, 0x2000
	s_add_u32 s46, s60, 0x80080
	s_addc_u32 s47, s61, 0
	s_add_i32 s48, s49, s73
	s_add_u32 s100, s60, 128
	s_addc_u32 s101, s61, 0
	global_load_lds_dwordx4 v154, s[100:101]
	s_mov_b32 m0, s48
	s_nop 0
	global_load_lds_dwordx4 v166, s[46:47]
	s_waitcnt vmcnt(5)
	s_waitcnt lgkmcnt(0)
	s_barrier
	s_setprio 1
	s_waitcnt lgkmcnt(0)
	v_mfma_f32_16x16x32_bf16 v[62:65], v[130:133], v[206:209], v[62:65]
	v_mfma_f32_16x16x32_bf16 v[58:61], v[138:141], v[206:209], v[58:61]
	v_mfma_f32_16x16x32_bf16 v[50:53], v[130:133], v[214:217], v[50:53]
	v_mfma_f32_16x16x32_bf16 v[42:45], v[138:141], v[214:217], v[42:45]
	v_mfma_f32_16x16x32_bf16 v[34:37], v[130:133], v[222:225], v[34:37]
	v_mfma_f32_16x16x32_bf16 v[26:29], v[138:141], v[222:225], v[26:29]
	s_add_i32 m0, s48, 0x2000
	s_nop 0
	global_load_lds_dwordx4 v154, s[46:47]
	v_mfma_f32_16x16x32_bf16 v[18:21], v[130:133], v[230:233], v[18:21]
	v_mfma_f32_16x16x32_bf16 v[10:13], v[138:141], v[230:233], v[10:13]
	v_mfma_f32_16x16x32_bf16 v[62:65], v[134:137], v[210:213], v[62:65]
	v_mfma_f32_16x16x32_bf16 v[58:61], v[142:145], v[210:213], v[58:61]
	v_mfma_f32_16x16x32_bf16 v[50:53], v[134:137], v[218:221], v[50:53]
	v_mfma_f32_16x16x32_bf16 v[42:45], v[142:145], v[218:221], v[42:45]
	v_mfma_f32_16x16x32_bf16 v[34:37], v[134:137], v[226:229], v[34:37]
	v_mfma_f32_16x16x32_bf16 v[26:29], v[142:145], v[226:229], v[26:29]
	v_mfma_f32_16x16x32_bf16 v[18:21], v[134:137], v[234:237], v[18:21]
	v_mfma_f32_16x16x32_bf16 v[10:13], v[142:145], v[234:237], v[10:13]
	s_mov_b32 m0, s78
	s_nop 0
	s_add_u32 s100, s68, 128
	s_addc_u32 s101, s69, 0
	global_load_lds_dwordx4 v150, s[100:101]
	s_setprio 0
	s_setprio 1
	v_mfma_f32_16x16x32_bf16 v[54:57], v[146:149], v[206:209], v[54:57]
	v_mfma_f32_16x16x32_bf16 v[46:49], v[178:181], v[206:209], v[46:49]
	v_mfma_f32_16x16x32_bf16 v[38:41], v[146:149], v[214:217], v[38:41]
	v_mfma_f32_16x16x32_bf16 v[30:33], v[178:181], v[214:217], v[30:33]
	v_mfma_f32_16x16x32_bf16 v[22:25], v[146:149], v[222:225], v[22:25]
	v_mfma_f32_16x16x32_bf16 v[14:17], v[178:181], v[222:225], v[14:17]
	v_mfma_f32_16x16x32_bf16 v[6:9], v[146:149], v[230:233], v[6:9]
	v_mfma_f32_16x16x32_bf16 v[2:5], v[178:181], v[230:233], v[2:5]
	v_mfma_f32_16x16x32_bf16 v[54:57], v[160:163], v[210:213], v[54:57]
	v_mfma_f32_16x16x32_bf16 v[46:49], v[182:185], v[210:213], v[46:49]
	s_mov_b32 m0, s79
	s_nop 0
	s_add_u32 s100, s68, 128
	s_addc_u32 s101, s69, 0
	global_load_lds_dwordx4 v152, s[100:101]
	v_mfma_f32_16x16x32_bf16 v[38:41], v[160:163], v[218:221], v[38:41]
	v_mfma_f32_16x16x32_bf16 v[30:33], v[182:185], v[218:221], v[30:33]
	v_mfma_f32_16x16x32_bf16 v[22:25], v[160:163], v[226:229], v[22:25]
	v_mfma_f32_16x16x32_bf16 v[14:17], v[182:185], v[226:229], v[14:17]
	v_mfma_f32_16x16x32_bf16 v[6:9], v[160:163], v[234:237], v[6:9]
	v_mfma_f32_16x16x32_bf16 v[2:5], v[182:185], v[234:237], v[2:5]
	s_setprio 0
	s_barrier
	s_add_i32 s84, s84, 2
	s_add_u32 s66, s66, 0x100
	s_addc_u32 s67, s67, 0
	s_add_u32 s82, s82, 0x100
	s_addc_u32 s83, s83, 0
	s_cmp_gt_u32 s84, 29
	s_cbranch_scc0 .LBB0_903
	s_and_b64 vcc, exec, s[10:11]
	s_cbranch_vccz .LBB0_906
	s_barrier

.LBB0_1112:
	s_add_u32 s46, s64, 0xffe00080
	s_addc_u32 s47, s65, -1
	s_add_i32 s48, 0, 0x10000
	s_cmpk_eq_i32 s84, 0x7c
	s_cselect_b32 s67, s19, s47
	s_cselect_b32 s66, s80, s46
	s_cselect_b32 s61, s17, s83
	s_cselect_b32 s60, s81, s82
	s_add_i32 s49, 0, 0x14000
	v_add_u32_e32 v142, s48, v182
	v_add_u32_e32 v164, s49, v182
	ds_read_b128 v[130:133], v142
	ds_read_b128 v[134:137], v142 offset:1024
	ds_read_b128 v[138:141], v142 offset:2048
	ds_read_b128 v[142:145], v142 offset:3072
	ds_read_b128 v[146:149], v164
	ds_read_b128 v[160:163], v164 offset:1024
	ds_read_b128 v[178:181], v164 offset:2048
	ds_read_b128 v[186:189], v164 offset:3072
	s_add_i32 m0, s63, 0xc000
	ds_read_b128 v[206:209], v184
	ds_read_b128 v[210:213], v184 offset:1024
	ds_read_b128 v[214:217], v184 offset:2048
	ds_read_b128 v[218:221], v184 offset:3072
	ds_read_b128 v[222:225], v184 offset:4096
	ds_read_b128 v[226:229], v184 offset:5120
	ds_read_b128 v[230:233], v184 offset:6144
	ds_read_b128 v[234:237], v184 offset:7168
	global_load_lds_dwordx4 v156, s[64:65]
	s_add_i32 m0, s63, 0xe000
	s_nop 0
	global_load_lds_dwordx4 v158, s[64:65]
	s_waitcnt vmcnt(8)
	s_waitcnt lgkmcnt(0)
	s_barrier
	s_setprio 1
	s_waitcnt lgkmcnt(0)
	v_mfma_f32_16x16x32_bf16 v[126:129], v[130:133], v[206:209], v[126:129]
	v_mfma_f32_16x16x32_bf16 v[122:125], v[138:141], v[206:209], v[122:125]
	v_mfma_f32_16x16x32_bf16 v[118:121], v[130:133], v[214:217], v[118:121]
	v_mfma_f32_16x16x32_bf16 v[114:117], v[138:141], v[214:217], v[114:117]
	v_mfma_f32_16x16x32_bf16 v[94:97], v[130:133], v[222:225], v[94:97]
	v_mfma_f32_16x16x32_bf16 v[90:93], v[138:141], v[222:225], v[90:93]
	v_mfma_f32_16x16x32_bf16 v[82:85], v[130:133], v[230:233], v[82:85]
	v_mfma_f32_16x16x32_bf16 v[74:77], v[138:141], v[230:233], v[74:77]
	v_mfma_f32_16x16x32_bf16 v[126:129], v[134:137], v[210:213], v[126:129]
	v_mfma_f32_16x16x32_bf16 v[122:125], v[142:145], v[210:213], v[122:125]
	v_mfma_f32_16x16x32_bf16 v[118:121], v[134:137], v[218:221], v[118:121]
	v_mfma_f32_16x16x32_bf16 v[114:117], v[142:145], v[218:221], v[114:117]
	v_mfma_f32_16x16x32_bf16 v[94:97], v[134:137], v[226:229], v[94:97]
	v_mfma_f32_16x16x32_bf16 v[90:93], v[142:145], v[226:229], v[90:93]
	v_mfma_f32_16x16x32_bf16 v[82:85], v[134:137], v[234:237], v[82:85]
	v_mfma_f32_16x16x32_bf16 v[74:77], v[142:145], v[234:237], v[74:77]
	s_setprio 0
	s_setprio 1
	v_mfma_f32_16x16x32_bf16 v[110:113], v[146:149], v[206:209], v[110:113]
	v_mfma_f32_16x16x32_bf16 v[106:109], v[178:181], v[206:209], v[106:109]
	v_mfma_f32_16x16x32_bf16 v[102:105], v[146:149], v[214:217], v[102:105]
	v_mfma_f32_16x16x32_bf16 v[98:101], v[178:181], v[214:217], v[98:101]
	v_mfma_f32_16x16x32_bf16 v[86:89], v[146:149], v[222:225], v[86:89]
	v_mfma_f32_16x16x32_bf16 v[78:81], v[178:181], v[222:225], v[78:81]
	v_mfma_f32_16x16x32_bf16 v[70:73], v[146:149], v[230:233], v[70:73]
	v_mfma_f32_16x16x32_bf16 v[66:69], v[178:181], v[230:233], v[66:69]
	v_mfma_f32_16x16x32_bf16 v[110:113], v[160:163], v[210:213], v[110:113]
	v_mfma_f32_16x16x32_bf16 v[106:109], v[186:189], v[210:213], v[106:109]
	v_mfma_f32_16x16x32_bf16 v[102:105], v[160:163], v[218:221], v[102:105]
	v_mfma_f32_16x16x32_bf16 v[98:101], v[186:189], v[218:221], v[98:101]
	v_mfma_f32_16x16x32_bf16 v[86:89], v[160:163], v[226:229], v[86:89]
	v_mfma_f32_16x16x32_bf16 v[78:81], v[186:189], v[226:229], v[78:81]
	v_mfma_f32_16x16x32_bf16 v[70:73], v[160:163], v[234:237], v[70:73]
	v_mfma_f32_16x16x32_bf16 v[66:69], v[186:189], v[234:237], v[66:69]
	s_setprio 0
	s_barrier
	s_add_i32 s46, s48, s72
	s_mov_b32 m0, s46
	ds_read_b128 v[206:209], v184 offset:16384
	ds_read_b128 v[210:213], v184 offset:17408
	ds_read_b128 v[214:217], v184 offset:18432
	ds_read_b128 v[218:221], v184 offset:19456
	ds_read_b128 v[222:225], v184 offset:20480
	ds_read_b128 v[226:229], v184 offset:21504
	ds_read_b128 v[230:233], v184 offset:22528
	ds_read_b128 v[234:237], v184 offset:23552
	global_load_lds_dwordx4 v166, s[60:61]
	s_add_i32 m0, s46, 0x2000
	s_add_u32 s46, s60, 0x200000
	s_addc_u32 s47, s61, 0
	s_add_i32 s48, s49, s72
	global_load_lds_dwordx4 v154, s[60:61]
	s_mov_b32 m0, s48
	s_nop 0
	global_load_lds_dwordx4 v166, s[46:47]
	s_waitcnt vmcnt(5)
	s_waitcnt lgkmcnt(0)
	s_barrier
	s_setprio 1
	s_waitcnt lgkmcnt(0)
	v_mfma_f32_16x16x32_bf16 v[62:65], v[130:133], v[206:209], v[62:65]
	v_mfma_f32_16x16x32_bf16 v[58:61], v[138:141], v[206:209], v[58:61]
	v_mfma_f32_16x16x32_bf16 v[50:53], v[130:133], v[214:217], v[50:53]
	v_mfma_f32_16x16x32_bf16 v[42:45], v[138:141], v[214:217], v[42:45]
	v_mfma_f32_16x16x32_bf16 v[34:37], v[130:133], v[222:225], v[34:37]
	v_mfma_f32_16x16x32_bf16 v[26:29], v[138:141], v[222:225], v[26:29]
	s_add_i32 m0, s48, 0x2000
	s_nop 0
	global_load_lds_dwordx4 v154, s[46:47]
	v_mfma_f32_16x16x32_bf16 v[18:21], v[130:133], v[230:233], v[18:21]
	v_mfma_f32_16x16x32_bf16 v[10:13], v[138:141], v[230:233], v[10:13]
	v_mfma_f32_16x16x32_bf16 v[62:65], v[134:137], v[210:213], v[62:65]
	v_mfma_f32_16x16x32_bf16 v[58:61], v[142:145], v[210:213], v[58:61]
	v_mfma_f32_16x16x32_bf16 v[50:53], v[134:137], v[218:221], v[50:53]
	v_mfma_f32_16x16x32_bf16 v[42:45], v[142:145], v[218:221], v[42:45]
	v_mfma_f32_16x16x32_bf16 v[34:37], v[134:137], v[226:229], v[34:37]
	v_mfma_f32_16x16x32_bf16 v[26:29], v[142:145], v[226:229], v[26:29]
	v_mfma_f32_16x16x32_bf16 v[18:21], v[134:137], v[234:237], v[18:21]
	v_mfma_f32_16x16x32_bf16 v[10:13], v[142:145], v[234:237], v[10:13]
	s_mov_b32 m0, s63
	s_nop 0
	global_load_lds_dwordx4 v150, s[66:67]
	s_setprio 0
	s_setprio 1
	v_mfma_f32_16x16x32_bf16 v[54:57], v[146:149], v[206:209], v[54:57]
	v_mfma_f32_16x16x32_bf16 v[46:49], v[178:181], v[206:209], v[46:49]
	v_mfma_f32_16x16x32_bf16 v[38:41], v[146:149], v[214:217], v[38:41]
	v_mfma_f32_16x16x32_bf16 v[30:33], v[178:181], v[214:217], v[30:33]
	v_mfma_f32_16x16x32_bf16 v[22:25], v[146:149], v[222:225], v[22:25]
	v_mfma_f32_16x16x32_bf16 v[14:17], v[178:181], v[222:225], v[14:17]
	v_mfma_f32_16x16x32_bf16 v[6:9], v[146:149], v[230:233], v[6:9]
	v_mfma_f32_16x16x32_bf16 v[2:5], v[178:181], v[230:233], v[2:5]
	v_mfma_f32_16x16x32_bf16 v[54:57], v[160:163], v[210:213], v[54:57]
	v_mfma_f32_16x16x32_bf16 v[46:49], v[186:189], v[210:213], v[46:49]
	s_mov_b32 m0, s73
	s_nop 0
	global_load_lds_dwordx4 v152, s[66:67]
	v_mfma_f32_16x16x32_bf16 v[38:41], v[160:163], v[218:221], v[38:41]
	v_mfma_f32_16x16x32_bf16 v[30:33], v[186:189], v[218:221], v[30:33]
	v_mfma_f32_16x16x32_bf16 v[22:25], v[160:163], v[226:229], v[22:25]
	v_mfma_f32_16x16x32_bf16 v[14:17], v[186:189], v[226:229], v[14:17]
	v_mfma_f32_16x16x32_bf16 v[6:9], v[160:163], v[234:237], v[6:9]
	v_mfma_f32_16x16x32_bf16 v[2:5], v[186:189], v[234:237], v[2:5]
	s_setprio 0
	s_barrier
	s_add_i32 s48, 0, 0x18000
	s_add_i32 s49, 0, 0x1c000
	v_add_u32_e32 v142, s48, v182
	v_add_u32_e32 v185, s49, v182
	ds_read_b128 v[130:133], v142
	ds_read_b128 v[134:137], v142 offset:1024
	ds_read_b128 v[138:141], v142 offset:2048
	ds_read_b128 v[142:145], v142 offset:3072
	ds_read_b128 v[146:149], v185
	ds_read_b128 v[160:163], v185 offset:1024
	ds_read_b128 v[178:181], v185 offset:2048
	ds_read_b128 v[186:189], v185 offset:3072
	s_add_u32 s46, s66, 0x200000
	s_addc_u32 s47, s67, 0
	s_mov_b32 m0, s74
	ds_read_b128 v[206:209], v184 offset:32768
	ds_read_b128 v[210:213], v184 offset:33792
	ds_read_b128 v[214:217], v184 offset:34816
	ds_read_b128 v[218:221], v184 offset:35840
	ds_read_b128 v[222:225], v184 offset:36864
	ds_read_b128 v[226:229], v184 offset:37888
	ds_read_b128 v[230:233], v184 offset:38912
	ds_read_b128 v[234:237], v184 offset:39936
	global_load_lds_dwordx4 v150, s[46:47]
	s_mov_b32 m0, s75
	s_nop 0
	global_load_lds_dwordx4 v152, s[46:47]
	s_waitcnt vmcnt(8)
	s_waitcnt lgkmcnt(0)
	s_barrier
	s_setprio 1
	s_waitcnt lgkmcnt(0)
	v_mfma_f32_16x16x32_bf16 v[126:129], v[130:133], v[206:209], v[126:129]
	v_mfma_f32_16x16x32_bf16 v[122:125], v[138:141], v[206:209], v[122:125]
	v_mfma_f32_16x16x32_bf16 v[118:121], v[130:133], v[214:217], v[118:121]
	v_mfma_f32_16x16x32_bf16 v[114:117], v[138:141], v[214:217], v[114:117]
	v_mfma_f32_16x16x32_bf16 v[94:97], v[130:133], v[222:225], v[94:97]
	v_mfma_f32_16x16x32_bf16 v[90:93], v[138:141], v[222:225], v[90:93]
	v_mfma_f32_16x16x32_bf16 v[82:85], v[130:133], v[230:233], v[82:85]
	v_mfma_f32_16x16x32_bf16 v[74:77], v[138:141], v[230:233], v[74:77]
	v_mfma_f32_16x16x32_bf16 v[126:129], v[134:137], v[210:213], v[126:129]
	v_mfma_f32_16x16x32_bf16 v[122:125], v[142:145], v[210:213], v[122:125]
	v_mfma_f32_16x16x32_bf16 v[118:121], v[134:137], v[218:221], v[118:121]
	v_mfma_f32_16x16x32_bf16 v[114:117], v[142:145], v[218:221], v[114:117]
	v_mfma_f32_16x16x32_bf16 v[94:97], v[134:137], v[226:229], v[94:97]
	v_mfma_f32_16x16x32_bf16 v[90:93], v[142:145], v[226:229], v[90:93]
	v_mfma_f32_16x16x32_bf16 v[82:85], v[134:137], v[234:237], v[82:85]
	v_mfma_f32_16x16x32_bf16 v[74:77], v[142:145], v[234:237], v[74:77]
	s_setprio 0
	s_setprio 1
	v_mfma_f32_16x16x32_bf16 v[110:113], v[146:149], v[206:209], v[110:113]
	v_mfma_f32_16x16x32_bf16 v[106:109], v[178:181], v[206:209], v[106:109]
	v_mfma_f32_16x16x32_bf16 v[102:105], v[146:149], v[214:217], v[102:105]
	v_mfma_f32_16x16x32_bf16 v[98:101], v[178:181], v[214:217], v[98:101]
	v_mfma_f32_16x16x32_bf16 v[86:89], v[146:149], v[222:225], v[86:89]
	v_mfma_f32_16x16x32_bf16 v[78:81], v[178:181], v[222:225], v[78:81]
	v_mfma_f32_16x16x32_bf16 v[70:73], v[146:149], v[230:233], v[70:73]
	v_mfma_f32_16x16x32_bf16 v[66:69], v[178:181], v[230:233], v[66:69]
	v_mfma_f32_16x16x32_bf16 v[110:113], v[160:163], v[210:213], v[110:113]
	v_mfma_f32_16x16x32_bf16 v[106:109], v[186:189], v[210:213], v[106:109]
	v_mfma_f32_16x16x32_bf16 v[102:105], v[160:163], v[218:221], v[102:105]
	v_mfma_f32_16x16x32_bf16 v[98:101], v[186:189], v[218:221], v[98:101]
	v_mfma_f32_16x16x32_bf16 v[86:89], v[160:163], v[226:229], v[86:89]
	v_mfma_f32_16x16x32_bf16 v[78:81], v[186:189], v[226:229], v[78:81]
	v_mfma_f32_16x16x32_bf16 v[70:73], v[160:163], v[234:237], v[70:73]
	v_mfma_f32_16x16x32_bf16 v[66:69], v[186:189], v[234:237], v[66:69]
	s_setprio 0
	s_barrier
	s_add_i32 s46, s48, s72
	s_mov_b32 m0, s46
	ds_read_b128 v[206:209], v184 offset:49152
	ds_read_b128 v[210:213], v184 offset:50176
	ds_read_b128 v[214:217], v184 offset:51200
	ds_read_b128 v[218:221], v184 offset:52224
	ds_read_b128 v[222:225], v184 offset:53248
	ds_read_b128 v[226:229], v184 offset:54272
	ds_read_b128 v[230:233], v184 offset:55296
	ds_read_b128 v[234:237], v184 offset:56320
	s_add_u32 s100, s60, 128
	s_addc_u32 s101, s61, 0
	global_load_lds_dwordx4 v166, s[100:101]
	s_add_i32 m0, s46, 0x2000
	s_add_u32 s46, s60, 0x200080
	s_addc_u32 s47, s61, 0
	s_add_i32 s48, s49, s72
	s_add_u32 s100, s60, 128
	s_addc_u32 s101, s61, 0
	global_load_lds_dwordx4 v154, s[100:101]
	s_mov_b32 m0, s48
	s_nop 0
	global_load_lds_dwordx4 v166, s[46:47]
	s_waitcnt vmcnt(5)
	s_waitcnt lgkmcnt(0)
	s_barrier
	s_setprio 1
	s_waitcnt lgkmcnt(0)
	v_mfma_f32_16x16x32_bf16 v[62:65], v[130:133], v[206:209], v[62:65]
	v_mfma_f32_16x16x32_bf16 v[58:61], v[138:141], v[206:209], v[58:61]
	v_mfma_f32_16x16x32_bf16 v[50:53], v[130:133], v[214:217], v[50:53]
	v_mfma_f32_16x16x32_bf16 v[42:45], v[138:141], v[214:217], v[42:45]
	v_mfma_f32_16x16x32_bf16 v[34:37], v[130:133], v[222:225], v[34:37]
	v_mfma_f32_16x16x32_bf16 v[26:29], v[138:141], v[222:225], v[26:29]
	s_add_i32 m0, s48, 0x2000
	s_nop 0
	global_load_lds_dwordx4 v154, s[46:47]
	v_mfma_f32_16x16x32_bf16 v[18:21], v[130:133], v[230:233], v[18:21]
	v_mfma_f32_16x16x32_bf16 v[10:13], v[138:141], v[230:233], v[10:13]
	v_mfma_f32_16x16x32_bf16 v[62:65], v[134:137], v[210:213], v[62:65]
	v_mfma_f32_16x16x32_bf16 v[58:61], v[142:145], v[210:213], v[58:61]
	v_mfma_f32_16x16x32_bf16 v[50:53], v[134:137], v[218:221], v[50:53]
	v_mfma_f32_16x16x32_bf16 v[42:45], v[142:145], v[218:221], v[42:45]
	v_mfma_f32_16x16x32_bf16 v[34:37], v[134:137], v[226:229], v[34:37]
	v_mfma_f32_16x16x32_bf16 v[26:29], v[142:145], v[226:229], v[26:29]
	v_mfma_f32_16x16x32_bf16 v[18:21], v[134:137], v[234:237], v[18:21]
	v_mfma_f32_16x16x32_bf16 v[10:13], v[142:145], v[234:237], v[10:13]
	s_mov_b32 m0, s76
	s_nop 0
	s_add_u32 s100, s66, 128
	s_addc_u32 s101, s67, 0
	global_load_lds_dwordx4 v150, s[100:101]
	s_setprio 0
	s_setprio 1
	v_mfma_f32_16x16x32_bf16 v[54:57], v[146:149], v[206:209], v[54:57]
	v_mfma_f32_16x16x32_bf16 v[46:49], v[178:181], v[206:209], v[46:49]
	v_mfma_f32_16x16x32_bf16 v[38:41], v[146:149], v[214:217], v[38:41]
	v_mfma_f32_16x16x32_bf16 v[30:33], v[178:181], v[214:217], v[30:33]
	v_mfma_f32_16x16x32_bf16 v[22:25], v[146:149], v[222:225], v[22:25]
	v_mfma_f32_16x16x32_bf16 v[14:17], v[178:181], v[222:225], v[14:17]
	v_mfma_f32_16x16x32_bf16 v[6:9], v[146:149], v[230:233], v[6:9]
	v_mfma_f32_16x16x32_bf16 v[2:5], v[178:181], v[230:233], v[2:5]
	v_mfma_f32_16x16x32_bf16 v[54:57], v[160:163], v[210:213], v[54:57]
	v_mfma_f32_16x16x32_bf16 v[46:49], v[186:189], v[210:213], v[46:49]
	s_mov_b32 m0, s77
	s_nop 0
	s_add_u32 s100, s66, 128
	s_addc_u32 s101, s67, 0
	global_load_lds_dwordx4 v152, s[100:101]
	v_mfma_f32_16x16x32_bf16 v[38:41], v[160:163], v[218:221], v[38:41]
	v_mfma_f32_16x16x32_bf16 v[30:33], v[186:189], v[218:221], v[30:33]
	v_mfma_f32_16x16x32_bf16 v[22:25], v[160:163], v[226:229], v[22:25]
	v_mfma_f32_16x16x32_bf16 v[14:17], v[186:189], v[226:229], v[14:17]
	v_mfma_f32_16x16x32_bf16 v[6:9], v[160:163], v[234:237], v[6:9]
	v_mfma_f32_16x16x32_bf16 v[2:5], v[186:189], v[234:237], v[2:5]
	s_setprio 0
	s_barrier
	s_add_i32 s84, s84, 2
	s_add_u32 s64, s64, 0x100
	s_addc_u32 s65, s65, 0
	s_add_u32 s82, s82, 0x100
	s_addc_u32 s83, s83, 0
	s_cmpk_gt_u32 s84, 0x7d
	s_cbranch_scc0 .LBB0_1112
	s_and_b64 vcc, exec, s[12:13]
	s_cbranch_vccz .LBB0_1115
	s_barrier

.LBB0_1138:
	s_add_u32 s46, s62, 0xffe00080
	s_addc_u32 s47, s63, -1
	s_add_i32 s48, 0, 0x10000
	s_cmpk_eq_i32 s82, 0x7c
	s_cselect_b32 s65, s17, s47
	s_cselect_b32 s64, s78, s46
	s_cselect_b32 s61, s13, s81
	s_cselect_b32 s60, s79, s80
	s_add_i32 s49, 0, 0x14000
	v_add_u32_e32 v142, s48, v186
	v_add_u32_e32 v164, s49, v186
	ds_read_b128 v[130:133], v142
	ds_read_b128 v[134:137], v142 offset:1024
	ds_read_b128 v[138:141], v142 offset:2048
	ds_read_b128 v[142:145], v142 offset:3072
	ds_read_b128 v[146:149], v164
	ds_read_b128 v[160:163], v164 offset:1024
	ds_read_b128 v[178:181], v164 offset:2048
	ds_read_b128 v[182:185], v164 offset:3072
	s_add_i32 m0, s71, 0xc000
	ds_read_b128 v[206:209], v188
	ds_read_b128 v[210:213], v188 offset:1024
	ds_read_b128 v[214:217], v188 offset:2048
	ds_read_b128 v[218:221], v188 offset:3072
	ds_read_b128 v[222:225], v188 offset:4096
	ds_read_b128 v[226:229], v188 offset:5120
	ds_read_b128 v[230:233], v188 offset:6144
	ds_read_b128 v[234:237], v188 offset:7168
	global_load_lds_dwordx4 v156, s[62:63]
	s_add_i32 m0, s71, 0xe000
	s_nop 0
	global_load_lds_dwordx4 v158, s[62:63]
	s_waitcnt vmcnt(8)
	s_waitcnt lgkmcnt(0)
	s_barrier
	s_setprio 1
	s_waitcnt lgkmcnt(0)
	v_mfma_f32_16x16x32_bf16 v[126:129], v[130:133], v[206:209], v[126:129]
	v_mfma_f32_16x16x32_bf16 v[122:125], v[138:141], v[206:209], v[122:125]
	v_mfma_f32_16x16x32_bf16 v[118:121], v[130:133], v[214:217], v[118:121]
	v_mfma_f32_16x16x32_bf16 v[110:113], v[138:141], v[214:217], v[110:113]
	v_mfma_f32_16x16x32_bf16 v[94:97], v[130:133], v[222:225], v[94:97]
	v_mfma_f32_16x16x32_bf16 v[90:93], v[138:141], v[222:225], v[90:93]
	v_mfma_f32_16x16x32_bf16 v[82:85], v[130:133], v[230:233], v[82:85]
	v_mfma_f32_16x16x32_bf16 v[74:77], v[138:141], v[230:233], v[74:77]
	v_mfma_f32_16x16x32_bf16 v[126:129], v[134:137], v[210:213], v[126:129]
	v_mfma_f32_16x16x32_bf16 v[122:125], v[142:145], v[210:213], v[122:125]
	v_mfma_f32_16x16x32_bf16 v[118:121], v[134:137], v[218:221], v[118:121]
	v_mfma_f32_16x16x32_bf16 v[110:113], v[142:145], v[218:221], v[110:113]
	v_mfma_f32_16x16x32_bf16 v[94:97], v[134:137], v[226:229], v[94:97]
	v_mfma_f32_16x16x32_bf16 v[90:93], v[142:145], v[226:229], v[90:93]
	v_mfma_f32_16x16x32_bf16 v[82:85], v[134:137], v[234:237], v[82:85]
	v_mfma_f32_16x16x32_bf16 v[74:77], v[142:145], v[234:237], v[74:77]
	s_setprio 0
	s_setprio 1
	v_mfma_f32_16x16x32_bf16 v[114:117], v[146:149], v[206:209], v[114:117]
	v_mfma_f32_16x16x32_bf16 v[106:109], v[178:181], v[206:209], v[106:109]
	v_mfma_f32_16x16x32_bf16 v[102:105], v[146:149], v[214:217], v[102:105]
	v_mfma_f32_16x16x32_bf16 v[98:101], v[178:181], v[214:217], v[98:101]
	v_mfma_f32_16x16x32_bf16 v[86:89], v[146:149], v[222:225], v[86:89]
	v_mfma_f32_16x16x32_bf16 v[78:81], v[178:181], v[222:225], v[78:81]
	v_mfma_f32_16x16x32_bf16 v[70:73], v[146:149], v[230:233], v[70:73]
	v_mfma_f32_16x16x32_bf16 v[66:69], v[178:181], v[230:233], v[66:69]
	v_mfma_f32_16x16x32_bf16 v[114:117], v[160:163], v[210:213], v[114:117]
	v_mfma_f32_16x16x32_bf16 v[106:109], v[182:185], v[210:213], v[106:109]
	v_mfma_f32_16x16x32_bf16 v[102:105], v[160:163], v[218:221], v[102:105]
	v_mfma_f32_16x16x32_bf16 v[98:101], v[182:185], v[218:221], v[98:101]
	v_mfma_f32_16x16x32_bf16 v[86:89], v[160:163], v[226:229], v[86:89]
	v_mfma_f32_16x16x32_bf16 v[78:81], v[182:185], v[226:229], v[78:81]
	v_mfma_f32_16x16x32_bf16 v[70:73], v[160:163], v[234:237], v[70:73]
	v_mfma_f32_16x16x32_bf16 v[66:69], v[182:185], v[234:237], v[66:69]
	s_setprio 0
	s_barrier
	s_add_i32 s46, s48, s70
	s_mov_b32 m0, s46
	ds_read_b128 v[206:209], v188 offset:16384
	ds_read_b128 v[210:213], v188 offset:17408
	ds_read_b128 v[214:217], v188 offset:18432
	ds_read_b128 v[218:221], v188 offset:19456
	ds_read_b128 v[222:225], v188 offset:20480
	ds_read_b128 v[226:229], v188 offset:21504
	ds_read_b128 v[230:233], v188 offset:22528
	ds_read_b128 v[234:237], v188 offset:23552
	global_load_lds_dwordx4 v166, s[60:61]
	s_add_i32 m0, s46, 0x2000
	s_add_u32 s46, s60, 0x200000
	s_addc_u32 s47, s61, 0
	s_add_i32 s48, s49, s70
	global_load_lds_dwordx4 v154, s[60:61]
	s_mov_b32 m0, s48
	s_nop 0
	global_load_lds_dwordx4 v166, s[46:47]
	s_waitcnt vmcnt(5)
	s_waitcnt lgkmcnt(0)
	s_barrier
	s_setprio 1
	s_waitcnt lgkmcnt(0)
	v_mfma_f32_16x16x32_bf16 v[62:65], v[130:133], v[206:209], v[62:65]
	v_mfma_f32_16x16x32_bf16 v[58:61], v[138:141], v[206:209], v[58:61]
	v_mfma_f32_16x16x32_bf16 v[50:53], v[130:133], v[214:217], v[50:53]
	v_mfma_f32_16x16x32_bf16 v[42:45], v[138:141], v[214:217], v[42:45]
	v_mfma_f32_16x16x32_bf16 v[34:37], v[130:133], v[222:225], v[34:37]
	v_mfma_f32_16x16x32_bf16 v[26:29], v[138:141], v[222:225], v[26:29]
	s_add_i32 m0, s48, 0x2000
	s_nop 0
	global_load_lds_dwordx4 v154, s[46:47]
	v_mfma_f32_16x16x32_bf16 v[18:21], v[130:133], v[230:233], v[18:21]
	v_mfma_f32_16x16x32_bf16 v[10:13], v[138:141], v[230:233], v[10:13]
	v_mfma_f32_16x16x32_bf16 v[62:65], v[134:137], v[210:213], v[62:65]
	v_mfma_f32_16x16x32_bf16 v[58:61], v[142:145], v[210:213], v[58:61]
	v_mfma_f32_16x16x32_bf16 v[50:53], v[134:137], v[218:221], v[50:53]
	v_mfma_f32_16x16x32_bf16 v[42:45], v[142:145], v[218:221], v[42:45]
	v_mfma_f32_16x16x32_bf16 v[34:37], v[134:137], v[226:229], v[34:37]
	v_mfma_f32_16x16x32_bf16 v[26:29], v[142:145], v[226:229], v[26:29]
	v_mfma_f32_16x16x32_bf16 v[18:21], v[134:137], v[234:237], v[18:21]
	v_mfma_f32_16x16x32_bf16 v[10:13], v[142:145], v[234:237], v[10:13]
	s_mov_b32 m0, s71
	s_nop 0
	global_load_lds_dwordx4 v150, s[64:65]
	s_setprio 0
	s_setprio 1
	v_mfma_f32_16x16x32_bf16 v[54:57], v[146:149], v[206:209], v[54:57]
	v_mfma_f32_16x16x32_bf16 v[46:49], v[178:181], v[206:209], v[46:49]
	v_mfma_f32_16x16x32_bf16 v[38:41], v[146:149], v[214:217], v[38:41]
	v_mfma_f32_16x16x32_bf16 v[30:33], v[178:181], v[214:217], v[30:33]
	v_mfma_f32_16x16x32_bf16 v[22:25], v[146:149], v[222:225], v[22:25]
	v_mfma_f32_16x16x32_bf16 v[14:17], v[178:181], v[222:225], v[14:17]
	v_mfma_f32_16x16x32_bf16 v[6:9], v[146:149], v[230:233], v[6:9]
	v_mfma_f32_16x16x32_bf16 v[2:5], v[178:181], v[230:233], v[2:5]
	v_mfma_f32_16x16x32_bf16 v[54:57], v[160:163], v[210:213], v[54:57]
	v_mfma_f32_16x16x32_bf16 v[46:49], v[182:185], v[210:213], v[46:49]
	s_mov_b32 m0, s72
	s_nop 0
	global_load_lds_dwordx4 v152, s[64:65]
	v_mfma_f32_16x16x32_bf16 v[38:41], v[160:163], v[218:221], v[38:41]
	v_mfma_f32_16x16x32_bf16 v[30:33], v[182:185], v[218:221], v[30:33]
	v_mfma_f32_16x16x32_bf16 v[22:25], v[160:163], v[226:229], v[22:25]
	v_mfma_f32_16x16x32_bf16 v[14:17], v[182:185], v[226:229], v[14:17]
	v_mfma_f32_16x16x32_bf16 v[6:9], v[160:163], v[234:237], v[6:9]
	v_mfma_f32_16x16x32_bf16 v[2:5], v[182:185], v[234:237], v[2:5]
	s_setprio 0
	s_barrier
	s_add_i32 s48, 0, 0x18000
	s_add_i32 s49, 0, 0x1c000
	v_add_u32_e32 v142, s48, v186
	v_add_u32_e32 v182, s49, v186
	ds_read_b128 v[130:133], v142
	ds_read_b128 v[134:137], v142 offset:1024
	ds_read_b128 v[138:141], v142 offset:2048
	ds_read_b128 v[142:145], v142 offset:3072
	ds_read_b128 v[146:149], v182
	ds_read_b128 v[160:163], v182 offset:1024
	ds_read_b128 v[178:181], v182 offset:2048
	ds_read_b128 v[182:185], v182 offset:3072
	s_add_u32 s46, s64, 0x200000
	s_addc_u32 s47, s65, 0
	s_mov_b32 m0, s73
	ds_read_b128 v[206:209], v188 offset:32768
	ds_read_b128 v[210:213], v188 offset:33792
	ds_read_b128 v[214:217], v188 offset:34816
	ds_read_b128 v[218:221], v188 offset:35840
	ds_read_b128 v[222:225], v188 offset:36864
	ds_read_b128 v[226:229], v188 offset:37888
	ds_read_b128 v[230:233], v188 offset:38912
	ds_read_b128 v[234:237], v188 offset:39936
	global_load_lds_dwordx4 v150, s[46:47]
	s_mov_b32 m0, s74
	s_nop 0
	global_load_lds_dwordx4 v152, s[46:47]
	s_waitcnt vmcnt(8)
	s_waitcnt lgkmcnt(0)
	s_barrier
	s_setprio 1
	s_waitcnt lgkmcnt(0)
	v_mfma_f32_16x16x32_bf16 v[126:129], v[130:133], v[206:209], v[126:129]
	v_mfma_f32_16x16x32_bf16 v[122:125], v[138:141], v[206:209], v[122:125]
	v_mfma_f32_16x16x32_bf16 v[118:121], v[130:133], v[214:217], v[118:121]
	v_mfma_f32_16x16x32_bf16 v[110:113], v[138:141], v[214:217], v[110:113]
	v_mfma_f32_16x16x32_bf16 v[94:97], v[130:133], v[222:225], v[94:97]
	v_mfma_f32_16x16x32_bf16 v[90:93], v[138:141], v[222:225], v[90:93]
	v_mfma_f32_16x16x32_bf16 v[82:85], v[130:133], v[230:233], v[82:85]
	v_mfma_f32_16x16x32_bf16 v[74:77], v[138:141], v[230:233], v[74:77]
	v_mfma_f32_16x16x32_bf16 v[126:129], v[134:137], v[210:213], v[126:129]
	v_mfma_f32_16x16x32_bf16 v[122:125], v[142:145], v[210:213], v[122:125]
	v_mfma_f32_16x16x32_bf16 v[118:121], v[134:137], v[218:221], v[118:121]
	v_mfma_f32_16x16x32_bf16 v[110:113], v[142:145], v[218:221], v[110:113]
	v_mfma_f32_16x16x32_bf16 v[94:97], v[134:137], v[226:229], v[94:97]
	v_mfma_f32_16x16x32_bf16 v[90:93], v[142:145], v[226:229], v[90:93]
	v_mfma_f32_16x16x32_bf16 v[82:85], v[134:137], v[234:237], v[82:85]
	v_mfma_f32_16x16x32_bf16 v[74:77], v[142:145], v[234:237], v[74:77]
	s_setprio 0
	s_setprio 1
	v_mfma_f32_16x16x32_bf16 v[114:117], v[146:149], v[206:209], v[114:117]
	v_mfma_f32_16x16x32_bf16 v[106:109], v[178:181], v[206:209], v[106:109]
	v_mfma_f32_16x16x32_bf16 v[102:105], v[146:149], v[214:217], v[102:105]
	v_mfma_f32_16x16x32_bf16 v[98:101], v[178:181], v[214:217], v[98:101]
	v_mfma_f32_16x16x32_bf16 v[86:89], v[146:149], v[222:225], v[86:89]
	v_mfma_f32_16x16x32_bf16 v[78:81], v[178:181], v[222:225], v[78:81]
	v_mfma_f32_16x16x32_bf16 v[70:73], v[146:149], v[230:233], v[70:73]
	v_mfma_f32_16x16x32_bf16 v[66:69], v[178:181], v[230:233], v[66:69]
	v_mfma_f32_16x16x32_bf16 v[114:117], v[160:163], v[210:213], v[114:117]
	v_mfma_f32_16x16x32_bf16 v[106:109], v[182:185], v[210:213], v[106:109]
	v_mfma_f32_16x16x32_bf16 v[102:105], v[160:163], v[218:221], v[102:105]
	v_mfma_f32_16x16x32_bf16 v[98:101], v[182:185], v[218:221], v[98:101]
	v_mfma_f32_16x16x32_bf16 v[86:89], v[160:163], v[226:229], v[86:89]
	v_mfma_f32_16x16x32_bf16 v[78:81], v[182:185], v[226:229], v[78:81]
	v_mfma_f32_16x16x32_bf16 v[70:73], v[160:163], v[234:237], v[70:73]
	v_mfma_f32_16x16x32_bf16 v[66:69], v[182:185], v[234:237], v[66:69]
	s_setprio 0
	s_barrier
	s_add_i32 s46, s48, s70
	s_mov_b32 m0, s46
	ds_read_b128 v[206:209], v188 offset:49152
	ds_read_b128 v[210:213], v188 offset:50176
	ds_read_b128 v[214:217], v188 offset:51200
	ds_read_b128 v[218:221], v188 offset:52224
	ds_read_b128 v[222:225], v188 offset:53248
	ds_read_b128 v[226:229], v188 offset:54272
	ds_read_b128 v[230:233], v188 offset:55296
	ds_read_b128 v[234:237], v188 offset:56320
	s_add_u32 s100, s60, 128
	s_addc_u32 s101, s61, 0
	global_load_lds_dwordx4 v166, s[100:101]
	s_add_i32 m0, s46, 0x2000
	s_add_u32 s46, s60, 0x200080
	s_addc_u32 s47, s61, 0
	s_add_i32 s48, s49, s70
	s_add_u32 s100, s60, 128
	s_addc_u32 s101, s61, 0
	global_load_lds_dwordx4 v154, s[100:101]
	s_mov_b32 m0, s48
	s_nop 0
	global_load_lds_dwordx4 v166, s[46:47]
	s_waitcnt vmcnt(5)
	s_waitcnt lgkmcnt(0)
	s_barrier
	s_setprio 1
	s_waitcnt lgkmcnt(0)
	v_mfma_f32_16x16x32_bf16 v[62:65], v[130:133], v[206:209], v[62:65]
	v_mfma_f32_16x16x32_bf16 v[58:61], v[138:141], v[206:209], v[58:61]
	v_mfma_f32_16x16x32_bf16 v[50:53], v[130:133], v[214:217], v[50:53]
	v_mfma_f32_16x16x32_bf16 v[42:45], v[138:141], v[214:217], v[42:45]
	v_mfma_f32_16x16x32_bf16 v[34:37], v[130:133], v[222:225], v[34:37]
	v_mfma_f32_16x16x32_bf16 v[26:29], v[138:141], v[222:225], v[26:29]
	s_add_i32 m0, s48, 0x2000
	s_nop 0
	global_load_lds_dwordx4 v154, s[46:47]
	v_mfma_f32_16x16x32_bf16 v[18:21], v[130:133], v[230:233], v[18:21]
	v_mfma_f32_16x16x32_bf16 v[10:13], v[138:141], v[230:233], v[10:13]
	v_mfma_f32_16x16x32_bf16 v[62:65], v[134:137], v[210:213], v[62:65]
	v_mfma_f32_16x16x32_bf16 v[58:61], v[142:145], v[210:213], v[58:61]
	v_mfma_f32_16x16x32_bf16 v[50:53], v[134:137], v[218:221], v[50:53]
	v_mfma_f32_16x16x32_bf16 v[42:45], v[142:145], v[218:221], v[42:45]
	v_mfma_f32_16x16x32_bf16 v[34:37], v[134:137], v[226:229], v[34:37]
	v_mfma_f32_16x16x32_bf16 v[26:29], v[142:145], v[226:229], v[26:29]
	v_mfma_f32_16x16x32_bf16 v[18:21], v[134:137], v[234:237], v[18:21]
	v_mfma_f32_16x16x32_bf16 v[10:13], v[142:145], v[234:237], v[10:13]
	s_mov_b32 m0, s75
	s_nop 0
	s_add_u32 s100, s64, 128
	s_addc_u32 s101, s65, 0
	global_load_lds_dwordx4 v150, s[100:101]
	s_setprio 0
	s_setprio 1
	v_mfma_f32_16x16x32_bf16 v[54:57], v[146:149], v[206:209], v[54:57]
	v_mfma_f32_16x16x32_bf16 v[46:49], v[178:181], v[206:209], v[46:49]
	v_mfma_f32_16x16x32_bf16 v[38:41], v[146:149], v[214:217], v[38:41]
	v_mfma_f32_16x16x32_bf16 v[30:33], v[178:181], v[214:217], v[30:33]
	v_mfma_f32_16x16x32_bf16 v[22:25], v[146:149], v[222:225], v[22:25]
	v_mfma_f32_16x16x32_bf16 v[14:17], v[178:181], v[222:225], v[14:17]
	v_mfma_f32_16x16x32_bf16 v[6:9], v[146:149], v[230:233], v[6:9]
	v_mfma_f32_16x16x32_bf16 v[2:5], v[178:181], v[230:233], v[2:5]
	v_mfma_f32_16x16x32_bf16 v[54:57], v[160:163], v[210:213], v[54:57]
	v_mfma_f32_16x16x32_bf16 v[46:49], v[182:185], v[210:213], v[46:49]
	s_mov_b32 m0, s76
	s_nop 0
	s_add_u32 s100, s64, 128
	s_addc_u32 s101, s65, 0
	global_load_lds_dwordx4 v152, s[100:101]
	v_mfma_f32_16x16x32_bf16 v[38:41], v[160:163], v[218:221], v[38:41]
	v_mfma_f32_16x16x32_bf16 v[30:33], v[182:185], v[218:221], v[30:33]
	v_mfma_f32_16x16x32_bf16 v[22:25], v[160:163], v[226:229], v[22:25]
	v_mfma_f32_16x16x32_bf16 v[14:17], v[182:185], v[226:229], v[14:17]
	v_mfma_f32_16x16x32_bf16 v[6:9], v[160:163], v[234:237], v[6:9]
	v_mfma_f32_16x16x32_bf16 v[2:5], v[182:185], v[234:237], v[2:5]
	s_setprio 0
	s_barrier
	s_add_i32 s82, s82, 2
	s_add_u32 s62, s62, 0x100
	s_addc_u32 s63, s63, 0
	s_add_u32 s80, s80, 0x100
	s_addc_u32 s81, s81, 0
	s_cmpk_gt_u32 s82, 0x7d
	s_cbranch_scc0 .LBB0_1138
	s_and_b64 vcc, exec, s[10:11]
	s_cbranch_vccz .LBB0_1141
	s_barrier
